# scan output y reduced across lanes with DPP and kept per lane in a register (no LDS park/reduce reads)
# speedup vs baseline: 1.0159x; 1.0006x over previous
; #define LAS __attribute__((address_space(3)))
; DI unsigned pack2(float lo, float hi) { f32x2 v = {lo, hi}; return __builtin_bit_cast(unsigned, __builtin_convertvector(v, bf16x2_t)); }
; DI void scan_item(PP p, int l, int item, LAS unsigned char* lds) {
;     ...
;     for (int c = 0; c < NCH; ++c) {
;         if (wid >= 4) { if (c + 1 < NCH) { fill(c + 1); if (c + 2 < NCH) gl(c + 2); } }
;         else {
;             const LAS float* sp = buf + ((c & 1) * T) * 384;
;             f32x4 Ar0, Ar1, Aw0, Aw1, Ak0, Ak1, Aa0, Aa1, Ab0, Ab1; float Avv;
;             f32x4 Br0, Br1, Bw0, Bw1, Bk0, Bk1, Ba0, Ba1, Bb0, Bb1; float Bvv;
;             SC_LD(A, sp);
;             const ptrdiff_t ystep = dir ? -512 : 512;
;             u16* Yl = Yp + (size_t)steprow(b, dir, c * T) * 512 + (ptrdiff_t)ks * ystep;
; #pragma nounroll
;             for (int st = 0; st < T; st += 2) {
;                 SC_LD(B, sp + (st + 1) * 384);
;                 SC_STEP(A, st);
;                 if (st + 2 < T) SC_LD(A, sp + (st + 2) * 384);
;                 SC_STEP(B, st + 1);
;                 if ((st & 6) == 6) {
;                     const LAS float* rp = ypl + (ks * 68 - lane) + (lane & ~7);
;                     const f32x4 q0 = *(const LAS f32x4*)rp, q1 = *(const LAS f32x4*)(rp + 4);
;                     Yl[(ptrdiff_t)(st - 6) * ystep] = (u16)(pack2(((q0[0] + q0[1]) + (q0[2] + q0[3])) + ((q1[0] + q1[1]) + (q1[2] + q1[3])), 0.f) & 0xffffu);
;                 }
;             }
.Lscan_row_done:
	s_ashr_i32 s7, s6, 31
	s_lshl_b64 s[6:7], s[6:7], 10
	v_lshl_add_u64 v[118:119], v[80:81], 0, s[6:7]
	s_lshl_b32 s8, s41, 4
	s_mov_b32 s9, s31
	v_mov_b32_e32 v126, v144
	v_mov_b32_e32 v127, v145
	v_mov_b32_e32 v124, v146
	v_mov_b32_e32 v125, v147
	v_mov_b32_e32 v122, v148
	v_mov_b32_e32 v123, v149
	v_mov_b32_e32 v120, v150
	v_mov_b32_e32 v121, v151
	ds_read_b128 v[40:43], v154 offset:1536
	ds_read_b128 v[44:47], v154 offset:1552
	ds_read_b128 v[64:67], v154 offset:2304
	ds_read_b128 v[68:71], v154 offset:2320
	ds_read_b128 v[56:59], v154 offset:2048
	ds_read_b128 v[60:63], v154 offset:2064
	ds_read_b128 v[72:75], v154 offset:2560
	ds_read_b128 v[76:79], v154 offset:2576
	ds_read_b32 v128, v153 offset:2816
	s_waitcnt lgkmcnt(9)
	v_pk_mul_f32 v[156:157], v[24:25], v[126:127]
	v_pk_mul_f32 v[90:91], v[28:29], v[122:123]
	v_pk_fma_f32 v[126:127], v[116:117], v[16:17], v[126:127] op_sel_hi:[0,1,1]
	v_pk_fma_f32 v[156:157], v[124:125], v[26:27], v[156:157]
	v_pk_fma_f32 v[90:91], v[120:121], v[30:31], v[90:91]
	v_pk_fma_f32 v[124:125], v[116:117], v[18:19], v[124:125] op_sel_hi:[0,1,1]
	v_pk_fma_f32 v[122:123], v[116:117], v[20:21], v[122:123] op_sel_hi:[0,1,1]
	v_pk_add_f32 v[156:157], v[156:157], v[90:91]
	v_pk_fma_f32 v[120:121], v[116:117], v[22:23], v[120:121] op_sel_hi:[0,1,1]
	v_add_f32_e32 v155, v156, v157
	s_nop 1
	v_add_f32_dpp v155, v155, v155 quad_perm:[1,0,3,2] row_mask:0xf bank_mask:0xf bound_ctrl:1
	s_nop 1
	v_add_f32_dpp v155, v155, v155 quad_perm:[2,3,0,1] row_mask:0xf bank_mask:0xf bound_ctrl:1
	s_nop 1
	v_add_f32_dpp v156, v155, v155 row_half_mirror row_mask:0xf bank_mask:0xf bound_ctrl:1
	v_pk_fma_f32 v[126:127], v[156:157], v[32:33], v[126:127] op_sel_hi:[0,1,1]
	v_pk_fma_f32 v[124:125], v[156:157], v[34:35], v[124:125] op_sel_hi:[0,1,1]
	v_pk_fma_f32 v[122:123], v[156:157], v[36:37], v[122:123] op_sel_hi:[0,1,1]
	v_pk_fma_f32 v[120:121], v[156:157], v[38:39], v[120:121] op_sel_hi:[0,1,1]
	ds_read_b128 v[24:27], v154 offset:3840
	ds_read_b128 v[28:31], v154 offset:3856
	ds_read_b128 v[16:19], v154 offset:3584
	ds_read_b128 v[20:23], v154 offset:3600
	ds_read_b128 v[32:35], v154 offset:4096
	ds_read_b128 v[36:39], v154 offset:4112
	ds_read_b32 v116, v153 offset:4352
	s_waitcnt lgkmcnt(7)
	v_pk_mul_f32 v[156:157], v[64:65], v[126:127]
	v_pk_mul_f32 v[90:91], v[68:69], v[122:123]
	v_pk_mul_f32 v[158:159], v[0:1], v[126:127]
	v_pk_fma_f32 v[156:157], v[124:125], v[66:67], v[156:157]
	v_pk_fma_f32 v[90:91], v[120:121], v[70:71], v[90:91]
	v_pk_fma_f32 v[158:159], v[124:125], v[2:3], v[158:159]
	v_pk_fma_f32 v[126:127], v[128:129], v[56:57], v[126:127] op_sel_hi:[0,1,1]
	v_pk_fma_f32 v[158:159], v[122:123], v[4:5], v[158:159]
	v_pk_fma_f32 v[124:125], v[128:129], v[58:59], v[124:125] op_sel_hi:[0,1,1]
	v_pk_add_f32 v[156:157], v[156:157], v[90:91]
	v_pk_fma_f32 v[158:159], v[120:121], v[6:7], v[158:159]
	v_add_f32_e32 v155, v156, v157
	v_pk_fma_f32 v[122:123], v[128:129], v[60:61], v[122:123] op_sel_hi:[0,1,1]
	v_pk_fma_f32 v[120:121], v[128:129], v[62:63], v[120:121] op_sel_hi:[0,1,1]
	ds_read_b128 v[0:3], v154 offset:3072
	ds_read_b128 v[4:7], v154 offset:3088
	v_add_f32_e32 v158, v158, v159
	v_add_f32_dpp v155, v155, v155 quad_perm:[1,0,3,2] row_mask:0xf bank_mask:0xf bound_ctrl:1
	s_mov_b32 s6, 0x1010101
	s_mov_b32 s7, 0x1010101
	v_add_f32_dpp v158, v158, v158 quad_perm:[1,0,3,2] row_mask:0xf bank_mask:0xf bound_ctrl:1
	v_add_f32_dpp v155, v155, v155 quad_perm:[2,3,0,1] row_mask:0xf bank_mask:0xf bound_ctrl:1
	s_nop 0
	v_add_f32_dpp v158, v158, v158 quad_perm:[2,3,0,1] row_mask:0xf bank_mask:0xf bound_ctrl:1
	v_add_f32_dpp v156, v155, v155 row_half_mirror row_mask:0xf bank_mask:0xf bound_ctrl:1
	v_pk_fma_f32 v[126:127], v[156:157], v[72:73], v[126:127] op_sel_hi:[0,1,1]
	v_pk_fma_f32 v[124:125], v[156:157], v[74:75], v[124:125] op_sel_hi:[0,1,1]
	v_add_f32_dpp v158, v158, v158 row_half_mirror row_mask:0xf bank_mask:0xf bound_ctrl:1
	v_pk_fma_f32 v[122:123], v[156:157], v[76:77], v[122:123] op_sel_hi:[0,1,1]
	v_pk_fma_f32 v[120:121], v[156:157], v[78:79], v[120:121] op_sel_hi:[0,1,1]
	v_cndmask_b32_e64 v94, v94, v158, s[6:7]
	ds_read_b128 v[64:67], v154 offset:5376
	ds_read_b128 v[68:71], v154 offset:5392
	ds_read_b128 v[56:59], v154 offset:5120
	ds_read_b128 v[60:63], v154 offset:5136
	ds_read_b128 v[72:75], v154 offset:5632
	ds_read_b128 v[76:79], v154 offset:5648
	ds_read_b32 v128, v153 offset:5888
	s_waitcnt lgkmcnt(7)
	v_pk_mul_f32 v[156:157], v[24:25], v[126:127]
	v_pk_mul_f32 v[90:91], v[28:29], v[122:123]
	v_pk_mul_f32 v[158:159], v[40:41], v[126:127]
	v_pk_fma_f32 v[156:157], v[124:125], v[26:27], v[156:157]
	v_pk_fma_f32 v[90:91], v[120:121], v[30:31], v[90:91]
	v_pk_fma_f32 v[158:159], v[124:125], v[42:43], v[158:159]
	v_pk_fma_f32 v[126:127], v[116:117], v[16:17], v[126:127] op_sel_hi:[0,1,1]
	v_pk_fma_f32 v[158:159], v[122:123], v[44:45], v[158:159]
	v_pk_fma_f32 v[124:125], v[116:117], v[18:19], v[124:125] op_sel_hi:[0,1,1]
	v_pk_add_f32 v[156:157], v[156:157], v[90:91]
	v_pk_fma_f32 v[158:159], v[120:121], v[46:47], v[158:159]
	v_add_f32_e32 v155, v156, v157
	v_pk_fma_f32 v[122:123], v[116:117], v[20:21], v[122:123] op_sel_hi:[0,1,1]
	v_pk_fma_f32 v[120:121], v[116:117], v[22:23], v[120:121] op_sel_hi:[0,1,1]
	ds_read_b128 v[40:43], v154 offset:4608
	ds_read_b128 v[44:47], v154 offset:4624
	v_add_f32_e32 v158, v158, v159
	v_add_f32_dpp v155, v155, v155 quad_perm:[1,0,3,2] row_mask:0xf bank_mask:0xf bound_ctrl:1
	s_mov_b32 s6, 0x2020202
	s_mov_b32 s7, 0x2020202
	v_add_f32_dpp v158, v158, v158 quad_perm:[1,0,3,2] row_mask:0xf bank_mask:0xf bound_ctrl:1
	v_add_f32_dpp v155, v155, v155 quad_perm:[2,3,0,1] row_mask:0xf bank_mask:0xf bound_ctrl:1
	s_nop 0
	v_add_f32_dpp v158, v158, v158 quad_perm:[2,3,0,1] row_mask:0xf bank_mask:0xf bound_ctrl:1
	v_add_f32_dpp v156, v155, v155 row_half_mirror row_mask:0xf bank_mask:0xf bound_ctrl:1
	v_pk_fma_f32 v[126:127], v[156:157], v[32:33], v[126:127] op_sel_hi:[0,1,1]
	v_pk_fma_f32 v[124:125], v[156:157], v[34:35], v[124:125] op_sel_hi:[0,1,1]
	v_add_f32_dpp v158, v158, v158 row_half_mirror row_mask:0xf bank_mask:0xf bound_ctrl:1
	v_pk_fma_f32 v[122:123], v[156:157], v[36:37], v[122:123] op_sel_hi:[0,1,1]
	v_pk_fma_f32 v[120:121], v[156:157], v[38:39], v[120:121] op_sel_hi:[0,1,1]
	v_cndmask_b32_e64 v94, v94, v158, s[6:7]
	ds_read_b128 v[24:27], v154 offset:6912
	ds_read_b128 v[28:31], v154 offset:6928
	ds_read_b128 v[16:19], v154 offset:6656
	ds_read_b128 v[20:23], v154 offset:6672
	ds_read_b128 v[32:35], v154 offset:7168
	ds_read_b128 v[36:39], v154 offset:7184
	ds_read_b32 v116, v153 offset:7424
	s_waitcnt lgkmcnt(7)
; #define LAS __attribute__((address_space(3)))
; DI unsigned pack2(float lo, float hi) { f32x2 v = {lo, hi}; return __builtin_bit_cast(unsigned, __builtin_convertvector(v, bf16x2_t)); }
; DI void scan_item(PP p, int l, int item, LAS unsigned char* lds) {
;     ...
;     for (int c = 0; c < NCH; ++c) {
;         if (wid >= 4) { if (c + 1 < NCH) { fill(c + 1); if (c + 2 < NCH) gl(c + 2); } }
;         else {
;             const LAS float* sp = buf + ((c & 1) * T) * 384;
;             f32x4 Ar0, Ar1, Aw0, Aw1, Ak0, Ak1, Aa0, Aa1, Ab0, Ab1; float Avv;
;             f32x4 Br0, Br1, Bw0, Bw1, Bk0, Bk1, Ba0, Ba1, Bb0, Bb1; float Bvv;
;             SC_LD(A, sp);
;             const ptrdiff_t ystep = dir ? -512 : 512;
;             u16* Yl = Yp + (size_t)steprow(b, dir, c * T) * 512 + (ptrdiff_t)ks * ystep;
; #pragma nounroll
;             for (int st = 0; st < T; st += 2) {
;                 SC_LD(B, sp + (st + 1) * 384);
;                 SC_STEP(A, st);
;                 if (st + 2 < T) SC_LD(A, sp + (st + 2) * 384);
;                 SC_STEP(B, st + 1);
;                 if ((st & 6) == 6) {
;                     const LAS float* rp = ypl + (ks * 68 - lane) + (lane & ~7);
;                     const f32x4 q0 = *(const LAS f32x4*)rp, q1 = *(const LAS f32x4*)(rp + 4);
;                     Yl[(ptrdiff_t)(st - 6) * ystep] = (u16)(pack2(((q0[0] + q0[1]) + (q0[2] + q0[3])) + ((q1[0] + q1[1]) + (q1[2] + q1[3])), 0.f) & 0xffffu);
;                 }
;             }
	v_pk_mul_f32 v[156:157], v[64:65], v[126:127]
	v_pk_mul_f32 v[90:91], v[68:69], v[122:123]
	v_pk_mul_f32 v[158:159], v[0:1], v[126:127]
	v_pk_fma_f32 v[156:157], v[124:125], v[66:67], v[156:157]
	v_pk_fma_f32 v[90:91], v[120:121], v[70:71], v[90:91]
	v_pk_fma_f32 v[158:159], v[124:125], v[2:3], v[158:159]
	v_pk_fma_f32 v[126:127], v[128:129], v[56:57], v[126:127] op_sel_hi:[0,1,1]
	v_pk_fma_f32 v[158:159], v[122:123], v[4:5], v[158:159]
	v_pk_fma_f32 v[124:125], v[128:129], v[58:59], v[124:125] op_sel_hi:[0,1,1]
	v_pk_add_f32 v[156:157], v[156:157], v[90:91]
	v_pk_fma_f32 v[158:159], v[120:121], v[6:7], v[158:159]
	v_add_f32_e32 v155, v156, v157
	v_pk_fma_f32 v[122:123], v[128:129], v[60:61], v[122:123] op_sel_hi:[0,1,1]
	v_pk_fma_f32 v[120:121], v[128:129], v[62:63], v[120:121] op_sel_hi:[0,1,1]
	ds_read_b128 v[0:3], v154 offset:6144
	ds_read_b128 v[4:7], v154 offset:6160
	v_add_f32_e32 v158, v158, v159
	v_add_f32_dpp v155, v155, v155 quad_perm:[1,0,3,2] row_mask:0xf bank_mask:0xf bound_ctrl:1
	s_mov_b32 s6, 0x4040404
	s_mov_b32 s7, 0x4040404
	v_add_f32_dpp v158, v158, v158 quad_perm:[1,0,3,2] row_mask:0xf bank_mask:0xf bound_ctrl:1
	v_add_f32_dpp v155, v155, v155 quad_perm:[2,3,0,1] row_mask:0xf bank_mask:0xf bound_ctrl:1
	s_nop 0
	v_add_f32_dpp v158, v158, v158 quad_perm:[2,3,0,1] row_mask:0xf bank_mask:0xf bound_ctrl:1
	v_add_f32_dpp v156, v155, v155 row_half_mirror row_mask:0xf bank_mask:0xf bound_ctrl:1
	v_pk_fma_f32 v[126:127], v[156:157], v[72:73], v[126:127] op_sel_hi:[0,1,1]
	v_pk_fma_f32 v[124:125], v[156:157], v[74:75], v[124:125] op_sel_hi:[0,1,1]
	v_add_f32_dpp v158, v158, v158 row_half_mirror row_mask:0xf bank_mask:0xf bound_ctrl:1
	v_pk_fma_f32 v[122:123], v[156:157], v[76:77], v[122:123] op_sel_hi:[0,1,1]
	v_pk_fma_f32 v[120:121], v[156:157], v[78:79], v[120:121] op_sel_hi:[0,1,1]
	v_cndmask_b32_e64 v94, v94, v158, s[6:7]
	ds_read_b128 v[64:67], v154 offset:8448
	ds_read_b128 v[68:71], v154 offset:8464
	ds_read_b128 v[56:59], v154 offset:8192
	ds_read_b128 v[60:63], v154 offset:8208
	ds_read_b128 v[72:75], v154 offset:8704
	ds_read_b128 v[76:79], v154 offset:8720
	ds_read_b32 v128, v153 offset:8960
	s_waitcnt lgkmcnt(7)
	v_pk_mul_f32 v[156:157], v[24:25], v[126:127]
	v_pk_mul_f32 v[90:91], v[28:29], v[122:123]
	v_pk_mul_f32 v[158:159], v[40:41], v[126:127]
	v_pk_fma_f32 v[156:157], v[124:125], v[26:27], v[156:157]
	v_pk_fma_f32 v[90:91], v[120:121], v[30:31], v[90:91]
	v_pk_fma_f32 v[158:159], v[124:125], v[42:43], v[158:159]
	v_pk_fma_f32 v[126:127], v[116:117], v[16:17], v[126:127] op_sel_hi:[0,1,1]
	v_pk_fma_f32 v[158:159], v[122:123], v[44:45], v[158:159]
	v_pk_fma_f32 v[124:125], v[116:117], v[18:19], v[124:125] op_sel_hi:[0,1,1]
	v_pk_add_f32 v[156:157], v[156:157], v[90:91]
	v_pk_fma_f32 v[158:159], v[120:121], v[46:47], v[158:159]
	v_add_f32_e32 v155, v156, v157
	v_pk_fma_f32 v[122:123], v[116:117], v[20:21], v[122:123] op_sel_hi:[0,1,1]
	v_pk_fma_f32 v[120:121], v[116:117], v[22:23], v[120:121] op_sel_hi:[0,1,1]
	ds_read_b128 v[40:43], v154 offset:7680
	ds_read_b128 v[44:47], v154 offset:7696
	v_add_f32_e32 v158, v158, v159
	v_add_f32_dpp v155, v155, v155 quad_perm:[1,0,3,2] row_mask:0xf bank_mask:0xf bound_ctrl:1
	s_mov_b32 s6, 0x8080808
	s_mov_b32 s7, 0x8080808
	v_add_f32_dpp v158, v158, v158 quad_perm:[1,0,3,2] row_mask:0xf bank_mask:0xf bound_ctrl:1
	v_add_f32_dpp v155, v155, v155 quad_perm:[2,3,0,1] row_mask:0xf bank_mask:0xf bound_ctrl:1
	s_nop 0
	v_add_f32_dpp v158, v158, v158 quad_perm:[2,3,0,1] row_mask:0xf bank_mask:0xf bound_ctrl:1
	v_add_f32_dpp v156, v155, v155 row_half_mirror row_mask:0xf bank_mask:0xf bound_ctrl:1
	v_pk_fma_f32 v[126:127], v[156:157], v[32:33], v[126:127] op_sel_hi:[0,1,1]
	v_pk_fma_f32 v[124:125], v[156:157], v[34:35], v[124:125] op_sel_hi:[0,1,1]
	v_add_f32_dpp v158, v158, v158 row_half_mirror row_mask:0xf bank_mask:0xf bound_ctrl:1
	v_pk_fma_f32 v[122:123], v[156:157], v[36:37], v[122:123] op_sel_hi:[0,1,1]
	v_pk_fma_f32 v[120:121], v[156:157], v[38:39], v[120:121] op_sel_hi:[0,1,1]
	v_cndmask_b32_e64 v94, v94, v158, s[6:7]
	ds_read_b128 v[24:27], v154 offset:9984
	ds_read_b128 v[28:31], v154 offset:10000
	ds_read_b128 v[16:19], v154 offset:9728
	ds_read_b128 v[20:23], v154 offset:9744
	ds_read_b128 v[32:35], v154 offset:10240
	ds_read_b128 v[36:39], v154 offset:10256
	ds_read_b32 v116, v153 offset:10496
	s_waitcnt lgkmcnt(7)
	v_pk_mul_f32 v[156:157], v[64:65], v[126:127]
	v_pk_mul_f32 v[90:91], v[68:69], v[122:123]
	v_pk_mul_f32 v[158:159], v[0:1], v[126:127]
	v_pk_fma_f32 v[156:157], v[124:125], v[66:67], v[156:157]
	v_pk_fma_f32 v[90:91], v[120:121], v[70:71], v[90:91]
	v_pk_fma_f32 v[158:159], v[124:125], v[2:3], v[158:159]
	v_pk_fma_f32 v[126:127], v[128:129], v[56:57], v[126:127] op_sel_hi:[0,1,1]
	v_pk_fma_f32 v[158:159], v[122:123], v[4:5], v[158:159]
	v_pk_fma_f32 v[124:125], v[128:129], v[58:59], v[124:125] op_sel_hi:[0,1,1]
	v_pk_add_f32 v[156:157], v[156:157], v[90:91]
	v_pk_fma_f32 v[158:159], v[120:121], v[6:7], v[158:159]
	v_add_f32_e32 v155, v156, v157
	v_pk_fma_f32 v[122:123], v[128:129], v[60:61], v[122:123] op_sel_hi:[0,1,1]
	v_pk_fma_f32 v[120:121], v[128:129], v[62:63], v[120:121] op_sel_hi:[0,1,1]
	ds_read_b128 v[0:3], v154 offset:9216
	ds_read_b128 v[4:7], v154 offset:9232
	v_add_f32_e32 v158, v158, v159
	v_add_f32_dpp v155, v155, v155 quad_perm:[1,0,3,2] row_mask:0xf bank_mask:0xf bound_ctrl:1
	s_mov_b32 s6, 0x10101010
	s_mov_b32 s7, 0x10101010
	v_add_f32_dpp v158, v158, v158 quad_perm:[1,0,3,2] row_mask:0xf bank_mask:0xf bound_ctrl:1
	v_add_f32_dpp v155, v155, v155 quad_perm:[2,3,0,1] row_mask:0xf bank_mask:0xf bound_ctrl:1
	s_nop 0
	v_add_f32_dpp v158, v158, v158 quad_perm:[2,3,0,1] row_mask:0xf bank_mask:0xf bound_ctrl:1
	v_add_f32_dpp v156, v155, v155 row_half_mirror row_mask:0xf bank_mask:0xf bound_ctrl:1
	v_pk_fma_f32 v[126:127], v[156:157], v[72:73], v[126:127] op_sel_hi:[0,1,1]
	v_pk_fma_f32 v[124:125], v[156:157], v[74:75], v[124:125] op_sel_hi:[0,1,1]
	v_add_f32_dpp v158, v158, v158 row_half_mirror row_mask:0xf bank_mask:0xf bound_ctrl:1
	v_pk_fma_f32 v[122:123], v[156:157], v[76:77], v[122:123] op_sel_hi:[0,1,1]
	v_pk_fma_f32 v[120:121], v[156:157], v[78:79], v[120:121] op_sel_hi:[0,1,1]
	v_cndmask_b32_e64 v94, v94, v158, s[6:7]
	ds_read_b128 v[64:67], v154 offset:11520
	ds_read_b128 v[68:71], v154 offset:11536
	ds_read_b128 v[56:59], v154 offset:11264
	ds_read_b128 v[60:63], v154 offset:11280
	ds_read_b128 v[72:75], v154 offset:11776
	ds_read_b128 v[76:79], v154 offset:11792
	ds_read_b32 v128, v153 offset:12032
	ds_read_b128 v[48:51], v154 offset:11008
	ds_read_b128 v[52:55], v154 offset:11024
	s_waitcnt lgkmcnt(9)
; #define LAS __attribute__((address_space(3)))
; DI unsigned pack2(float lo, float hi) { f32x2 v = {lo, hi}; return __builtin_bit_cast(unsigned, __builtin_convertvector(v, bf16x2_t)); }
; DI void scan_item(PP p, int l, int item, LAS unsigned char* lds) {
;     ...
;     for (int c = 0; c < NCH; ++c) {
;         if (wid >= 4) { if (c + 1 < NCH) { fill(c + 1); if (c + 2 < NCH) gl(c + 2); } }
;         else {
;             const LAS float* sp = buf + ((c & 1) * T) * 384;
;             f32x4 Ar0, Ar1, Aw0, Aw1, Ak0, Ak1, Aa0, Aa1, Ab0, Ab1; float Avv;
;             f32x4 Br0, Br1, Bw0, Bw1, Bk0, Bk1, Ba0, Ba1, Bb0, Bb1; float Bvv;
;             SC_LD(A, sp);
;             const ptrdiff_t ystep = dir ? -512 : 512;
;             u16* Yl = Yp + (size_t)steprow(b, dir, c * T) * 512 + (ptrdiff_t)ks * ystep;
; #pragma nounroll
;             for (int st = 0; st < T; st += 2) {
;                 SC_LD(B, sp + (st + 1) * 384);
;                 SC_STEP(A, st);
;                 if (st + 2 < T) SC_LD(A, sp + (st + 2) * 384);
;                 SC_STEP(B, st + 1);
;                 if ((st & 6) == 6) {
;                     const LAS float* rp = ypl + (ks * 68 - lane) + (lane & ~7);
;                     const f32x4 q0 = *(const LAS f32x4*)rp, q1 = *(const LAS f32x4*)(rp + 4);
;                     Yl[(ptrdiff_t)(st - 6) * ystep] = (u16)(pack2(((q0[0] + q0[1]) + (q0[2] + q0[3])) + ((q1[0] + q1[1]) + (q1[2] + q1[3])), 0.f) & 0xffffu);
;                 }
;             }
	v_pk_mul_f32 v[156:157], v[24:25], v[126:127]
	v_pk_mul_f32 v[90:91], v[28:29], v[122:123]
	v_pk_mul_f32 v[158:159], v[40:41], v[126:127]
	v_pk_fma_f32 v[156:157], v[124:125], v[26:27], v[156:157]
	v_pk_fma_f32 v[90:91], v[120:121], v[30:31], v[90:91]
	v_pk_fma_f32 v[158:159], v[124:125], v[42:43], v[158:159]
	v_pk_fma_f32 v[126:127], v[116:117], v[16:17], v[126:127] op_sel_hi:[0,1,1]
	v_pk_fma_f32 v[158:159], v[122:123], v[44:45], v[158:159]
	v_pk_fma_f32 v[124:125], v[116:117], v[18:19], v[124:125] op_sel_hi:[0,1,1]
	v_pk_add_f32 v[156:157], v[156:157], v[90:91]
	v_pk_fma_f32 v[158:159], v[120:121], v[46:47], v[158:159]
	v_add_f32_e32 v155, v156, v157
	v_pk_fma_f32 v[122:123], v[116:117], v[20:21], v[122:123] op_sel_hi:[0,1,1]
	v_pk_fma_f32 v[120:121], v[116:117], v[22:23], v[120:121] op_sel_hi:[0,1,1]
	ds_read_b128 v[40:43], v154 offset:10752
	ds_read_b128 v[44:47], v154 offset:10768
	v_add_f32_e32 v158, v158, v159
	v_add_f32_dpp v155, v155, v155 quad_perm:[1,0,3,2] row_mask:0xf bank_mask:0xf bound_ctrl:1
	s_mov_b32 s6, 0x20202020
	s_mov_b32 s7, 0x20202020
	v_add_f32_dpp v158, v158, v158 quad_perm:[1,0,3,2] row_mask:0xf bank_mask:0xf bound_ctrl:1
	v_add_f32_dpp v155, v155, v155 quad_perm:[2,3,0,1] row_mask:0xf bank_mask:0xf bound_ctrl:1
	s_nop 0
	v_add_f32_dpp v158, v158, v158 quad_perm:[2,3,0,1] row_mask:0xf bank_mask:0xf bound_ctrl:1
	v_add_f32_dpp v156, v155, v155 row_half_mirror row_mask:0xf bank_mask:0xf bound_ctrl:1
	v_pk_fma_f32 v[126:127], v[156:157], v[32:33], v[126:127] op_sel_hi:[0,1,1]
	v_pk_fma_f32 v[124:125], v[156:157], v[34:35], v[124:125] op_sel_hi:[0,1,1]
	v_add_f32_dpp v158, v158, v158 row_half_mirror row_mask:0xf bank_mask:0xf bound_ctrl:1
	v_pk_fma_f32 v[122:123], v[156:157], v[36:37], v[122:123] op_sel_hi:[0,1,1]
	v_pk_fma_f32 v[120:121], v[156:157], v[38:39], v[120:121] op_sel_hi:[0,1,1]
	v_cndmask_b32_e64 v94, v94, v158, s[6:7]
	ds_read_b128 v[24:27], v154 offset:13056
	ds_read_b128 v[28:31], v154 offset:13072
	ds_read_b128 v[16:19], v154 offset:12800
	ds_read_b128 v[20:23], v154 offset:12816
	ds_read_b128 v[32:35], v154 offset:13312
	ds_read_b128 v[36:39], v154 offset:13328
	ds_read_b32 v116, v153 offset:13568
	s_waitcnt lgkmcnt(7)
	v_pk_mul_f32 v[156:157], v[64:65], v[126:127]
	v_pk_mul_f32 v[90:91], v[68:69], v[122:123]
	v_pk_mul_f32 v[158:159], v[0:1], v[126:127]
	v_pk_fma_f32 v[156:157], v[124:125], v[66:67], v[156:157]
	v_pk_fma_f32 v[90:91], v[120:121], v[70:71], v[90:91]
	v_pk_fma_f32 v[158:159], v[124:125], v[2:3], v[158:159]
	v_pk_fma_f32 v[126:127], v[128:129], v[56:57], v[126:127] op_sel_hi:[0,1,1]
	v_pk_fma_f32 v[158:159], v[122:123], v[4:5], v[158:159]
	v_pk_fma_f32 v[124:125], v[128:129], v[58:59], v[124:125] op_sel_hi:[0,1,1]
	v_pk_add_f32 v[156:157], v[156:157], v[90:91]
	v_pk_fma_f32 v[158:159], v[120:121], v[6:7], v[158:159]
	v_add_f32_e32 v155, v156, v157
	v_pk_fma_f32 v[122:123], v[128:129], v[60:61], v[122:123] op_sel_hi:[0,1,1]
	v_pk_fma_f32 v[120:121], v[128:129], v[62:63], v[120:121] op_sel_hi:[0,1,1]
	ds_read_b128 v[0:3], v154 offset:12288
	ds_read_b128 v[4:7], v154 offset:12304
	v_add_f32_e32 v158, v158, v159
	v_add_f32_dpp v155, v155, v155 quad_perm:[1,0,3,2] row_mask:0xf bank_mask:0xf bound_ctrl:1
	s_mov_b32 s6, 0x40404040
	s_mov_b32 s7, 0x40404040
	v_add_f32_dpp v158, v158, v158 quad_perm:[1,0,3,2] row_mask:0xf bank_mask:0xf bound_ctrl:1
	v_add_f32_dpp v155, v155, v155 quad_perm:[2,3,0,1] row_mask:0xf bank_mask:0xf bound_ctrl:1
	s_nop 0
	v_add_f32_dpp v158, v158, v158 quad_perm:[2,3,0,1] row_mask:0xf bank_mask:0xf bound_ctrl:1
	v_add_f32_dpp v156, v155, v155 row_half_mirror row_mask:0xf bank_mask:0xf bound_ctrl:1
	v_pk_fma_f32 v[126:127], v[156:157], v[72:73], v[126:127] op_sel_hi:[0,1,1]
	v_pk_fma_f32 v[124:125], v[156:157], v[74:75], v[124:125] op_sel_hi:[0,1,1]
	v_add_f32_dpp v158, v158, v158 row_half_mirror row_mask:0xf bank_mask:0xf bound_ctrl:1
	v_pk_fma_f32 v[122:123], v[156:157], v[76:77], v[122:123] op_sel_hi:[0,1,1]
	v_pk_fma_f32 v[120:121], v[156:157], v[78:79], v[120:121] op_sel_hi:[0,1,1]
	v_cndmask_b32_e64 v94, v94, v158, s[6:7]
	v_pk_mul_f32 v[158:159], v[40:41], v[126:127]
	s_nop 0
	v_pk_fma_f32 v[158:159], v[124:125], v[42:43], v[158:159]
	s_nop 0
	v_pk_fma_f32 v[158:159], v[122:123], v[44:45], v[158:159]
	s_nop 0
	v_pk_fma_f32 v[158:159], v[120:121], v[46:47], v[158:159]
	s_nop 0
	v_add_f32_e32 v158, v158, v159
	s_mov_b32 s6, 0x80808080
	s_mov_b32 s7, 0x80808080
	v_add_f32_dpp v158, v158, v158 quad_perm:[1,0,3,2] row_mask:0xf bank_mask:0xf bound_ctrl:1
	s_nop 1
	v_add_f32_dpp v158, v158, v158 quad_perm:[2,3,0,1] row_mask:0xf bank_mask:0xf bound_ctrl:1
	s_nop 1
	v_add_f32_dpp v158, v158, v158 row_half_mirror row_mask:0xf bank_mask:0xf bound_ctrl:1
	v_pk_mul_f32 v[126:127], v[48:49], v[126:127]
	v_pk_mul_f32 v[124:125], v[50:51], v[124:125]
	v_pk_mul_f32 v[122:123], v[52:53], v[122:123]
	v_pk_mul_f32 v[120:121], v[54:55], v[120:121]
	v_cndmask_b32_e64 v94, v94, v158, s[6:7]
	ds_read_b128 v[40:43], v154 offset:13824
	ds_read_b128 v[44:47], v154 offset:13840
	ds_read_b128 v[64:67], v154 offset:14592
	ds_read_b128 v[68:71], v154 offset:14608
	ds_read_b128 v[56:59], v154 offset:14336
	ds_read_b128 v[60:63], v154 offset:14352
	ds_read_b128 v[72:75], v154 offset:14848
	ds_read_b128 v[76:79], v154 offset:14864
	ds_read_b32 v128, v153 offset:15104
	s_waitcnt lgkmcnt(9)
; #define LAS __attribute__((address_space(3)))
; DI unsigned pack2(float lo, float hi) { f32x2 v = {lo, hi}; return __builtin_bit_cast(unsigned, __builtin_convertvector(v, bf16x2_t)); }
; DI void scan_item(PP p, int l, int item, LAS unsigned char* lds) {
;     ...
;     for (int c = 0; c < NCH; ++c) {
;         if (wid >= 4) { if (c + 1 < NCH) { fill(c + 1); if (c + 2 < NCH) gl(c + 2); } }
;         else {
;             const LAS float* sp = buf + ((c & 1) * T) * 384;
;             f32x4 Ar0, Ar1, Aw0, Aw1, Ak0, Ak1, Aa0, Aa1, Ab0, Ab1; float Avv;
;             f32x4 Br0, Br1, Bw0, Bw1, Bk0, Bk1, Ba0, Ba1, Bb0, Bb1; float Bvv;
;             SC_LD(A, sp);
;             const ptrdiff_t ystep = dir ? -512 : 512;
;             u16* Yl = Yp + (size_t)steprow(b, dir, c * T) * 512 + (ptrdiff_t)ks * ystep;
; #pragma nounroll
;             for (int st = 0; st < T; st += 2) {
;                 SC_LD(B, sp + (st + 1) * 384);
;                 SC_STEP(A, st);
;                 if (st + 2 < T) SC_LD(A, sp + (st + 2) * 384);
;                 SC_STEP(B, st + 1);
;                 if ((st & 6) == 6) {
;                     const LAS float* rp = ypl + (ks * 68 - lane) + (lane & ~7);
;                     const f32x4 q0 = *(const LAS f32x4*)rp, q1 = *(const LAS f32x4*)(rp + 4);
;                     Yl[(ptrdiff_t)(st - 6) * ystep] = (u16)(pack2(((q0[0] + q0[1]) + (q0[2] + q0[3])) + ((q1[0] + q1[1]) + (q1[2] + q1[3])), 0.f) & 0xffffu);
;                 }
;             }
	v_pk_mul_f32 v[156:157], v[24:25], v[126:127]
	v_pk_mul_f32 v[90:91], v[28:29], v[122:123]
	v_pk_fma_f32 v[126:127], v[116:117], v[16:17], v[126:127] op_sel_hi:[0,1,1]
	v_pk_fma_f32 v[156:157], v[124:125], v[26:27], v[156:157]
	v_pk_fma_f32 v[90:91], v[120:121], v[30:31], v[90:91]
	v_pk_fma_f32 v[124:125], v[116:117], v[18:19], v[124:125] op_sel_hi:[0,1,1]
	v_pk_fma_f32 v[122:123], v[116:117], v[20:21], v[122:123] op_sel_hi:[0,1,1]
	v_pk_add_f32 v[156:157], v[156:157], v[90:91]
	v_pk_fma_f32 v[120:121], v[116:117], v[22:23], v[120:121] op_sel_hi:[0,1,1]
	v_add_f32_e32 v155, v156, v157
	s_nop 1
	v_add_f32_dpp v155, v155, v155 quad_perm:[1,0,3,2] row_mask:0xf bank_mask:0xf bound_ctrl:1
	s_nop 1
	v_add_f32_dpp v155, v155, v155 quad_perm:[2,3,0,1] row_mask:0xf bank_mask:0xf bound_ctrl:1
	s_nop 1
	v_add_f32_dpp v156, v155, v155 row_half_mirror row_mask:0xf bank_mask:0xf bound_ctrl:1
	v_pk_fma_f32 v[126:127], v[156:157], v[32:33], v[126:127] op_sel_hi:[0,1,1]
	v_pk_fma_f32 v[124:125], v[156:157], v[34:35], v[124:125] op_sel_hi:[0,1,1]
	v_pk_fma_f32 v[122:123], v[156:157], v[36:37], v[122:123] op_sel_hi:[0,1,1]
	v_pk_fma_f32 v[120:121], v[156:157], v[38:39], v[120:121] op_sel_hi:[0,1,1]
	v_cvt_pk_bf16_f32 v82, v94, v94
	global_store_short v[118:119], v82, off
	v_lshl_add_u64 v[118:119], s[8:9], 0, v[118:119]
	ds_read_b128 v[24:27], v154 offset:16128
	ds_read_b128 v[28:31], v154 offset:16144
	ds_read_b128 v[16:19], v154 offset:15872
	ds_read_b128 v[20:23], v154 offset:15888
	ds_read_b128 v[32:35], v154 offset:16384
	ds_read_b128 v[36:39], v154 offset:16400
	ds_read_b32 v116, v153 offset:16640
	s_waitcnt lgkmcnt(7)
	v_pk_mul_f32 v[156:157], v[64:65], v[126:127]
	v_pk_mul_f32 v[90:91], v[68:69], v[122:123]
	v_pk_mul_f32 v[158:159], v[0:1], v[126:127]
	v_pk_fma_f32 v[156:157], v[124:125], v[66:67], v[156:157]
	v_pk_fma_f32 v[90:91], v[120:121], v[70:71], v[90:91]
	v_pk_fma_f32 v[158:159], v[124:125], v[2:3], v[158:159]
	v_pk_fma_f32 v[126:127], v[128:129], v[56:57], v[126:127] op_sel_hi:[0,1,1]
	v_pk_fma_f32 v[158:159], v[122:123], v[4:5], v[158:159]
	v_pk_fma_f32 v[124:125], v[128:129], v[58:59], v[124:125] op_sel_hi:[0,1,1]
	v_pk_add_f32 v[156:157], v[156:157], v[90:91]
	v_pk_fma_f32 v[158:159], v[120:121], v[6:7], v[158:159]
	v_add_f32_e32 v155, v156, v157
	v_pk_fma_f32 v[122:123], v[128:129], v[60:61], v[122:123] op_sel_hi:[0,1,1]
	v_pk_fma_f32 v[120:121], v[128:129], v[62:63], v[120:121] op_sel_hi:[0,1,1]
	ds_read_b128 v[0:3], v154 offset:15360
	ds_read_b128 v[4:7], v154 offset:15376
	v_add_f32_e32 v158, v158, v159
	v_add_f32_dpp v155, v155, v155 quad_perm:[1,0,3,2] row_mask:0xf bank_mask:0xf bound_ctrl:1
	s_mov_b32 s6, 0x1010101
	s_mov_b32 s7, 0x1010101
	v_add_f32_dpp v158, v158, v158 quad_perm:[1,0,3,2] row_mask:0xf bank_mask:0xf bound_ctrl:1
	v_add_f32_dpp v155, v155, v155 quad_perm:[2,3,0,1] row_mask:0xf bank_mask:0xf bound_ctrl:1
	s_nop 0
	v_add_f32_dpp v158, v158, v158 quad_perm:[2,3,0,1] row_mask:0xf bank_mask:0xf bound_ctrl:1
	v_add_f32_dpp v156, v155, v155 row_half_mirror row_mask:0xf bank_mask:0xf bound_ctrl:1
	v_pk_fma_f32 v[126:127], v[156:157], v[72:73], v[126:127] op_sel_hi:[0,1,1]
	v_pk_fma_f32 v[124:125], v[156:157], v[74:75], v[124:125] op_sel_hi:[0,1,1]
	v_add_f32_dpp v158, v158, v158 row_half_mirror row_mask:0xf bank_mask:0xf bound_ctrl:1
	v_pk_fma_f32 v[122:123], v[156:157], v[76:77], v[122:123] op_sel_hi:[0,1,1]
	v_pk_fma_f32 v[120:121], v[156:157], v[78:79], v[120:121] op_sel_hi:[0,1,1]
	v_cndmask_b32_e64 v94, v94, v158, s[6:7]
	ds_read_b128 v[64:67], v154 offset:17664
	ds_read_b128 v[68:71], v154 offset:17680
	ds_read_b128 v[56:59], v154 offset:17408
	ds_read_b128 v[60:63], v154 offset:17424
	ds_read_b128 v[72:75], v154 offset:17920
	ds_read_b128 v[76:79], v154 offset:17936
	ds_read_b32 v128, v153 offset:18176
	s_waitcnt lgkmcnt(7)
	v_pk_mul_f32 v[156:157], v[24:25], v[126:127]
	v_pk_mul_f32 v[90:91], v[28:29], v[122:123]
	v_pk_mul_f32 v[158:159], v[40:41], v[126:127]
	v_pk_fma_f32 v[156:157], v[124:125], v[26:27], v[156:157]
	v_pk_fma_f32 v[90:91], v[120:121], v[30:31], v[90:91]
	v_pk_fma_f32 v[158:159], v[124:125], v[42:43], v[158:159]
	v_pk_fma_f32 v[126:127], v[116:117], v[16:17], v[126:127] op_sel_hi:[0,1,1]
	v_pk_fma_f32 v[158:159], v[122:123], v[44:45], v[158:159]
	v_pk_fma_f32 v[124:125], v[116:117], v[18:19], v[124:125] op_sel_hi:[0,1,1]
	v_pk_add_f32 v[156:157], v[156:157], v[90:91]
	v_pk_fma_f32 v[158:159], v[120:121], v[46:47], v[158:159]
	v_add_f32_e32 v155, v156, v157
	v_pk_fma_f32 v[122:123], v[116:117], v[20:21], v[122:123] op_sel_hi:[0,1,1]
	v_pk_fma_f32 v[120:121], v[116:117], v[22:23], v[120:121] op_sel_hi:[0,1,1]
	ds_read_b128 v[40:43], v154 offset:16896
	ds_read_b128 v[44:47], v154 offset:16912
	v_add_f32_e32 v158, v158, v159
	v_add_f32_dpp v155, v155, v155 quad_perm:[1,0,3,2] row_mask:0xf bank_mask:0xf bound_ctrl:1
	s_mov_b32 s6, 0x2020202
	s_mov_b32 s7, 0x2020202
	v_add_f32_dpp v158, v158, v158 quad_perm:[1,0,3,2] row_mask:0xf bank_mask:0xf bound_ctrl:1
	v_add_f32_dpp v155, v155, v155 quad_perm:[2,3,0,1] row_mask:0xf bank_mask:0xf bound_ctrl:1
	s_nop 0
	v_add_f32_dpp v158, v158, v158 quad_perm:[2,3,0,1] row_mask:0xf bank_mask:0xf bound_ctrl:1
	v_add_f32_dpp v156, v155, v155 row_half_mirror row_mask:0xf bank_mask:0xf bound_ctrl:1
	v_pk_fma_f32 v[126:127], v[156:157], v[32:33], v[126:127] op_sel_hi:[0,1,1]
	v_pk_fma_f32 v[124:125], v[156:157], v[34:35], v[124:125] op_sel_hi:[0,1,1]
	v_add_f32_dpp v158, v158, v158 row_half_mirror row_mask:0xf bank_mask:0xf bound_ctrl:1
	v_pk_fma_f32 v[122:123], v[156:157], v[36:37], v[122:123] op_sel_hi:[0,1,1]
	v_pk_fma_f32 v[120:121], v[156:157], v[38:39], v[120:121] op_sel_hi:[0,1,1]
	v_cndmask_b32_e64 v94, v94, v158, s[6:7]
	ds_read_b128 v[24:27], v154 offset:19200
	ds_read_b128 v[28:31], v154 offset:19216
	ds_read_b128 v[16:19], v154 offset:18944
	ds_read_b128 v[20:23], v154 offset:18960
	ds_read_b128 v[32:35], v154 offset:19456
	ds_read_b128 v[36:39], v154 offset:19472
	ds_read_b32 v116, v153 offset:19712
	s_waitcnt lgkmcnt(7)
; #define LAS __attribute__((address_space(3)))
; DI unsigned pack2(float lo, float hi) { f32x2 v = {lo, hi}; return __builtin_bit_cast(unsigned, __builtin_convertvector(v, bf16x2_t)); }
; DI void scan_item(PP p, int l, int item, LAS unsigned char* lds) {
;     ...
;     for (int c = 0; c < NCH; ++c) {
;         if (wid >= 4) { if (c + 1 < NCH) { fill(c + 1); if (c + 2 < NCH) gl(c + 2); } }
;         else {
;             const LAS float* sp = buf + ((c & 1) * T) * 384;
;             f32x4 Ar0, Ar1, Aw0, Aw1, Ak0, Ak1, Aa0, Aa1, Ab0, Ab1; float Avv;
;             f32x4 Br0, Br1, Bw0, Bw1, Bk0, Bk1, Ba0, Ba1, Bb0, Bb1; float Bvv;
;             SC_LD(A, sp);
;             const ptrdiff_t ystep = dir ? -512 : 512;
;             u16* Yl = Yp + (size_t)steprow(b, dir, c * T) * 512 + (ptrdiff_t)ks * ystep;
; #pragma nounroll
;             for (int st = 0; st < T; st += 2) {
;                 SC_LD(B, sp + (st + 1) * 384);
;                 SC_STEP(A, st);
;                 if (st + 2 < T) SC_LD(A, sp + (st + 2) * 384);
;                 SC_STEP(B, st + 1);
;                 if ((st & 6) == 6) {
;                     const LAS float* rp = ypl + (ks * 68 - lane) + (lane & ~7);
;                     const f32x4 q0 = *(const LAS f32x4*)rp, q1 = *(const LAS f32x4*)(rp + 4);
;                     Yl[(ptrdiff_t)(st - 6) * ystep] = (u16)(pack2(((q0[0] + q0[1]) + (q0[2] + q0[3])) + ((q1[0] + q1[1]) + (q1[2] + q1[3])), 0.f) & 0xffffu);
;                 }
;             }
	v_pk_mul_f32 v[156:157], v[64:65], v[126:127]
	v_pk_mul_f32 v[90:91], v[68:69], v[122:123]
	v_pk_mul_f32 v[158:159], v[0:1], v[126:127]
	v_pk_fma_f32 v[156:157], v[124:125], v[66:67], v[156:157]
	v_pk_fma_f32 v[90:91], v[120:121], v[70:71], v[90:91]
	v_pk_fma_f32 v[158:159], v[124:125], v[2:3], v[158:159]
	v_pk_fma_f32 v[126:127], v[128:129], v[56:57], v[126:127] op_sel_hi:[0,1,1]
	v_pk_fma_f32 v[158:159], v[122:123], v[4:5], v[158:159]
	v_pk_fma_f32 v[124:125], v[128:129], v[58:59], v[124:125] op_sel_hi:[0,1,1]
	v_pk_add_f32 v[156:157], v[156:157], v[90:91]
	v_pk_fma_f32 v[158:159], v[120:121], v[6:7], v[158:159]
	v_add_f32_e32 v155, v156, v157
	v_pk_fma_f32 v[122:123], v[128:129], v[60:61], v[122:123] op_sel_hi:[0,1,1]
	v_pk_fma_f32 v[120:121], v[128:129], v[62:63], v[120:121] op_sel_hi:[0,1,1]
	ds_read_b128 v[0:3], v154 offset:18432
	ds_read_b128 v[4:7], v154 offset:18448
	v_add_f32_e32 v158, v158, v159
	v_add_f32_dpp v155, v155, v155 quad_perm:[1,0,3,2] row_mask:0xf bank_mask:0xf bound_ctrl:1
	s_mov_b32 s6, 0x4040404
	s_mov_b32 s7, 0x4040404
	v_add_f32_dpp v158, v158, v158 quad_perm:[1,0,3,2] row_mask:0xf bank_mask:0xf bound_ctrl:1
	v_add_f32_dpp v155, v155, v155 quad_perm:[2,3,0,1] row_mask:0xf bank_mask:0xf bound_ctrl:1
	s_nop 0
	v_add_f32_dpp v158, v158, v158 quad_perm:[2,3,0,1] row_mask:0xf bank_mask:0xf bound_ctrl:1
	v_add_f32_dpp v156, v155, v155 row_half_mirror row_mask:0xf bank_mask:0xf bound_ctrl:1
	v_pk_fma_f32 v[126:127], v[156:157], v[72:73], v[126:127] op_sel_hi:[0,1,1]
	v_pk_fma_f32 v[124:125], v[156:157], v[74:75], v[124:125] op_sel_hi:[0,1,1]
	v_add_f32_dpp v158, v158, v158 row_half_mirror row_mask:0xf bank_mask:0xf bound_ctrl:1
	v_pk_fma_f32 v[122:123], v[156:157], v[76:77], v[122:123] op_sel_hi:[0,1,1]
	v_pk_fma_f32 v[120:121], v[156:157], v[78:79], v[120:121] op_sel_hi:[0,1,1]
	v_cndmask_b32_e64 v94, v94, v158, s[6:7]
	ds_read_b128 v[64:67], v154 offset:20736
	ds_read_b128 v[68:71], v154 offset:20752
	ds_read_b128 v[56:59], v154 offset:20480
	ds_read_b128 v[60:63], v154 offset:20496
	ds_read_b128 v[72:75], v154 offset:20992
	ds_read_b128 v[76:79], v154 offset:21008
	ds_read_b32 v128, v153 offset:21248
	s_waitcnt lgkmcnt(7)
	v_pk_mul_f32 v[156:157], v[24:25], v[126:127]
	v_pk_mul_f32 v[90:91], v[28:29], v[122:123]
	v_pk_mul_f32 v[158:159], v[40:41], v[126:127]
	v_pk_fma_f32 v[156:157], v[124:125], v[26:27], v[156:157]
	v_pk_fma_f32 v[90:91], v[120:121], v[30:31], v[90:91]
	v_pk_fma_f32 v[158:159], v[124:125], v[42:43], v[158:159]
	v_pk_fma_f32 v[126:127], v[116:117], v[16:17], v[126:127] op_sel_hi:[0,1,1]
	v_pk_fma_f32 v[158:159], v[122:123], v[44:45], v[158:159]
	v_pk_fma_f32 v[124:125], v[116:117], v[18:19], v[124:125] op_sel_hi:[0,1,1]
	v_pk_add_f32 v[156:157], v[156:157], v[90:91]
	v_pk_fma_f32 v[158:159], v[120:121], v[46:47], v[158:159]
	v_add_f32_e32 v155, v156, v157
	v_pk_fma_f32 v[122:123], v[116:117], v[20:21], v[122:123] op_sel_hi:[0,1,1]
	v_pk_fma_f32 v[120:121], v[116:117], v[22:23], v[120:121] op_sel_hi:[0,1,1]
	ds_read_b128 v[40:43], v154 offset:19968
	ds_read_b128 v[44:47], v154 offset:19984
	v_add_f32_e32 v158, v158, v159
	v_add_f32_dpp v155, v155, v155 quad_perm:[1,0,3,2] row_mask:0xf bank_mask:0xf bound_ctrl:1
	s_mov_b32 s6, 0x8080808
	s_mov_b32 s7, 0x8080808
	v_add_f32_dpp v158, v158, v158 quad_perm:[1,0,3,2] row_mask:0xf bank_mask:0xf bound_ctrl:1
	v_add_f32_dpp v155, v155, v155 quad_perm:[2,3,0,1] row_mask:0xf bank_mask:0xf bound_ctrl:1
	s_nop 0
	v_add_f32_dpp v158, v158, v158 quad_perm:[2,3,0,1] row_mask:0xf bank_mask:0xf bound_ctrl:1
	v_add_f32_dpp v156, v155, v155 row_half_mirror row_mask:0xf bank_mask:0xf bound_ctrl:1
	v_pk_fma_f32 v[126:127], v[156:157], v[32:33], v[126:127] op_sel_hi:[0,1,1]
	v_pk_fma_f32 v[124:125], v[156:157], v[34:35], v[124:125] op_sel_hi:[0,1,1]
	v_add_f32_dpp v158, v158, v158 row_half_mirror row_mask:0xf bank_mask:0xf bound_ctrl:1
	v_pk_fma_f32 v[122:123], v[156:157], v[36:37], v[122:123] op_sel_hi:[0,1,1]
	v_pk_fma_f32 v[120:121], v[156:157], v[38:39], v[120:121] op_sel_hi:[0,1,1]
	v_cndmask_b32_e64 v94, v94, v158, s[6:7]
	ds_read_b128 v[24:27], v154 offset:22272
	ds_read_b128 v[28:31], v154 offset:22288
	ds_read_b128 v[16:19], v154 offset:22016
	ds_read_b128 v[20:23], v154 offset:22032
	ds_read_b128 v[32:35], v154 offset:22528
	ds_read_b128 v[36:39], v154 offset:22544
	ds_read_b32 v116, v153 offset:22784
	s_waitcnt lgkmcnt(7)
	v_pk_mul_f32 v[156:157], v[64:65], v[126:127]
	v_pk_mul_f32 v[90:91], v[68:69], v[122:123]
	v_pk_mul_f32 v[158:159], v[0:1], v[126:127]
	v_pk_fma_f32 v[156:157], v[124:125], v[66:67], v[156:157]
	v_pk_fma_f32 v[90:91], v[120:121], v[70:71], v[90:91]
	v_pk_fma_f32 v[158:159], v[124:125], v[2:3], v[158:159]
	v_pk_fma_f32 v[126:127], v[128:129], v[56:57], v[126:127] op_sel_hi:[0,1,1]
	v_pk_fma_f32 v[158:159], v[122:123], v[4:5], v[158:159]
	v_pk_fma_f32 v[124:125], v[128:129], v[58:59], v[124:125] op_sel_hi:[0,1,1]
	v_pk_add_f32 v[156:157], v[156:157], v[90:91]
	v_pk_fma_f32 v[158:159], v[120:121], v[6:7], v[158:159]
	v_add_f32_e32 v155, v156, v157
	v_pk_fma_f32 v[122:123], v[128:129], v[60:61], v[122:123] op_sel_hi:[0,1,1]
	v_pk_fma_f32 v[120:121], v[128:129], v[62:63], v[120:121] op_sel_hi:[0,1,1]
	ds_read_b128 v[0:3], v154 offset:21504
	ds_read_b128 v[4:7], v154 offset:21520
	v_add_f32_e32 v158, v158, v159
	v_add_f32_dpp v155, v155, v155 quad_perm:[1,0,3,2] row_mask:0xf bank_mask:0xf bound_ctrl:1
	s_mov_b32 s6, 0x10101010
	s_mov_b32 s7, 0x10101010
	v_add_f32_dpp v158, v158, v158 quad_perm:[1,0,3,2] row_mask:0xf bank_mask:0xf bound_ctrl:1
	v_add_f32_dpp v155, v155, v155 quad_perm:[2,3,0,1] row_mask:0xf bank_mask:0xf bound_ctrl:1
	s_nop 0
	v_add_f32_dpp v158, v158, v158 quad_perm:[2,3,0,1] row_mask:0xf bank_mask:0xf bound_ctrl:1
	v_add_f32_dpp v156, v155, v155 row_half_mirror row_mask:0xf bank_mask:0xf bound_ctrl:1
	v_pk_fma_f32 v[126:127], v[156:157], v[72:73], v[126:127] op_sel_hi:[0,1,1]
	v_pk_fma_f32 v[124:125], v[156:157], v[74:75], v[124:125] op_sel_hi:[0,1,1]
	v_add_f32_dpp v158, v158, v158 row_half_mirror row_mask:0xf bank_mask:0xf bound_ctrl:1
	v_pk_fma_f32 v[122:123], v[156:157], v[76:77], v[122:123] op_sel_hi:[0,1,1]
	v_pk_fma_f32 v[120:121], v[156:157], v[78:79], v[120:121] op_sel_hi:[0,1,1]
	v_cndmask_b32_e64 v94, v94, v158, s[6:7]
	ds_read_b128 v[64:67], v154 offset:23808
	ds_read_b128 v[68:71], v154 offset:23824
	ds_read_b128 v[56:59], v154 offset:23552
	ds_read_b128 v[60:63], v154 offset:23568
	ds_read_b128 v[72:75], v154 offset:24064
	ds_read_b128 v[76:79], v154 offset:24080
	ds_read_b32 v128, v153 offset:24320
	ds_read_b128 v[48:51], v154 offset:23296
	ds_read_b128 v[52:55], v154 offset:23312
	s_waitcnt lgkmcnt(9)
; #define LAS __attribute__((address_space(3)))
; DI unsigned pack2(float lo, float hi) { f32x2 v = {lo, hi}; return __builtin_bit_cast(unsigned, __builtin_convertvector(v, bf16x2_t)); }
; DI void scan_item(PP p, int l, int item, LAS unsigned char* lds) {
;     ...
;     for (int c = 0; c < NCH; ++c) {
;         if (wid >= 4) { if (c + 1 < NCH) { fill(c + 1); if (c + 2 < NCH) gl(c + 2); } }
;         else {
;             const LAS float* sp = buf + ((c & 1) * T) * 384;
;             f32x4 Ar0, Ar1, Aw0, Aw1, Ak0, Ak1, Aa0, Aa1, Ab0, Ab1; float Avv;
;             f32x4 Br0, Br1, Bw0, Bw1, Bk0, Bk1, Ba0, Ba1, Bb0, Bb1; float Bvv;
;             SC_LD(A, sp);
;             const ptrdiff_t ystep = dir ? -512 : 512;
;             u16* Yl = Yp + (size_t)steprow(b, dir, c * T) * 512 + (ptrdiff_t)ks * ystep;
; #pragma nounroll
;             for (int st = 0; st < T; st += 2) {
;                 SC_LD(B, sp + (st + 1) * 384);
;                 SC_STEP(A, st);
;                 if (st + 2 < T) SC_LD(A, sp + (st + 2) * 384);
;                 SC_STEP(B, st + 1);
;                 if ((st & 6) == 6) {
;                     const LAS float* rp = ypl + (ks * 68 - lane) + (lane & ~7);
;                     const f32x4 q0 = *(const LAS f32x4*)rp, q1 = *(const LAS f32x4*)(rp + 4);
;                     Yl[(ptrdiff_t)(st - 6) * ystep] = (u16)(pack2(((q0[0] + q0[1]) + (q0[2] + q0[3])) + ((q1[0] + q1[1]) + (q1[2] + q1[3])), 0.f) & 0xffffu);
;                 }
;             }
	v_pk_mul_f32 v[156:157], v[24:25], v[126:127]
	v_pk_mul_f32 v[90:91], v[28:29], v[122:123]
	v_pk_mul_f32 v[158:159], v[40:41], v[126:127]
	v_pk_fma_f32 v[156:157], v[124:125], v[26:27], v[156:157]
	v_pk_fma_f32 v[90:91], v[120:121], v[30:31], v[90:91]
	v_pk_fma_f32 v[158:159], v[124:125], v[42:43], v[158:159]
	v_pk_fma_f32 v[126:127], v[116:117], v[16:17], v[126:127] op_sel_hi:[0,1,1]
	v_pk_fma_f32 v[158:159], v[122:123], v[44:45], v[158:159]
	v_pk_fma_f32 v[124:125], v[116:117], v[18:19], v[124:125] op_sel_hi:[0,1,1]
	v_pk_add_f32 v[156:157], v[156:157], v[90:91]
	v_pk_fma_f32 v[158:159], v[120:121], v[46:47], v[158:159]
	v_add_f32_e32 v155, v156, v157
	v_pk_fma_f32 v[122:123], v[116:117], v[20:21], v[122:123] op_sel_hi:[0,1,1]
	v_pk_fma_f32 v[120:121], v[116:117], v[22:23], v[120:121] op_sel_hi:[0,1,1]
	ds_read_b128 v[40:43], v154 offset:23040
	ds_read_b128 v[44:47], v154 offset:23056
	v_add_f32_e32 v158, v158, v159
	v_add_f32_dpp v155, v155, v155 quad_perm:[1,0,3,2] row_mask:0xf bank_mask:0xf bound_ctrl:1
	s_mov_b32 s6, 0x20202020
	s_mov_b32 s7, 0x20202020
	v_add_f32_dpp v158, v158, v158 quad_perm:[1,0,3,2] row_mask:0xf bank_mask:0xf bound_ctrl:1
	v_add_f32_dpp v155, v155, v155 quad_perm:[2,3,0,1] row_mask:0xf bank_mask:0xf bound_ctrl:1
	s_nop 0
	v_add_f32_dpp v158, v158, v158 quad_perm:[2,3,0,1] row_mask:0xf bank_mask:0xf bound_ctrl:1
	v_add_f32_dpp v156, v155, v155 row_half_mirror row_mask:0xf bank_mask:0xf bound_ctrl:1
	v_pk_fma_f32 v[126:127], v[156:157], v[32:33], v[126:127] op_sel_hi:[0,1,1]
	v_pk_fma_f32 v[124:125], v[156:157], v[34:35], v[124:125] op_sel_hi:[0,1,1]
	v_add_f32_dpp v158, v158, v158 row_half_mirror row_mask:0xf bank_mask:0xf bound_ctrl:1
	v_pk_fma_f32 v[122:123], v[156:157], v[36:37], v[122:123] op_sel_hi:[0,1,1]
	v_pk_fma_f32 v[120:121], v[156:157], v[38:39], v[120:121] op_sel_hi:[0,1,1]
	v_cndmask_b32_e64 v94, v94, v158, s[6:7]
	ds_read_b128 v[24:27], v154 offset:25344
	ds_read_b128 v[28:31], v154 offset:25360
	ds_read_b128 v[16:19], v154 offset:25088
	ds_read_b128 v[20:23], v154 offset:25104
	ds_read_b128 v[32:35], v154 offset:25600
	ds_read_b128 v[36:39], v154 offset:25616
	ds_read_b32 v116, v153 offset:25856
	s_waitcnt lgkmcnt(7)
	v_pk_mul_f32 v[156:157], v[64:65], v[126:127]
	v_pk_mul_f32 v[90:91], v[68:69], v[122:123]
	v_pk_mul_f32 v[158:159], v[0:1], v[126:127]
	v_pk_fma_f32 v[156:157], v[124:125], v[66:67], v[156:157]
	v_pk_fma_f32 v[90:91], v[120:121], v[70:71], v[90:91]
	v_pk_fma_f32 v[158:159], v[124:125], v[2:3], v[158:159]
	v_pk_fma_f32 v[126:127], v[128:129], v[56:57], v[126:127] op_sel_hi:[0,1,1]
	v_pk_fma_f32 v[158:159], v[122:123], v[4:5], v[158:159]
	v_pk_fma_f32 v[124:125], v[128:129], v[58:59], v[124:125] op_sel_hi:[0,1,1]
	v_pk_add_f32 v[156:157], v[156:157], v[90:91]
	v_pk_fma_f32 v[158:159], v[120:121], v[6:7], v[158:159]
	v_add_f32_e32 v155, v156, v157
	v_pk_fma_f32 v[122:123], v[128:129], v[60:61], v[122:123] op_sel_hi:[0,1,1]
	v_pk_fma_f32 v[120:121], v[128:129], v[62:63], v[120:121] op_sel_hi:[0,1,1]
	ds_read_b128 v[0:3], v154 offset:24576
	ds_read_b128 v[4:7], v154 offset:24592
	v_add_f32_e32 v158, v158, v159
	v_add_f32_dpp v155, v155, v155 quad_perm:[1,0,3,2] row_mask:0xf bank_mask:0xf bound_ctrl:1
	s_mov_b32 s6, 0x40404040
	s_mov_b32 s7, 0x40404040
	v_add_f32_dpp v158, v158, v158 quad_perm:[1,0,3,2] row_mask:0xf bank_mask:0xf bound_ctrl:1
	v_add_f32_dpp v155, v155, v155 quad_perm:[2,3,0,1] row_mask:0xf bank_mask:0xf bound_ctrl:1
	s_nop 0
	v_add_f32_dpp v158, v158, v158 quad_perm:[2,3,0,1] row_mask:0xf bank_mask:0xf bound_ctrl:1
	v_add_f32_dpp v156, v155, v155 row_half_mirror row_mask:0xf bank_mask:0xf bound_ctrl:1
	v_pk_fma_f32 v[126:127], v[156:157], v[72:73], v[126:127] op_sel_hi:[0,1,1]
	v_pk_fma_f32 v[124:125], v[156:157], v[74:75], v[124:125] op_sel_hi:[0,1,1]
	v_add_f32_dpp v158, v158, v158 row_half_mirror row_mask:0xf bank_mask:0xf bound_ctrl:1
	v_pk_fma_f32 v[122:123], v[156:157], v[76:77], v[122:123] op_sel_hi:[0,1,1]
	v_pk_fma_f32 v[120:121], v[156:157], v[78:79], v[120:121] op_sel_hi:[0,1,1]
	v_cndmask_b32_e64 v94, v94, v158, s[6:7]
	v_pk_mul_f32 v[158:159], v[40:41], v[126:127]
	s_nop 0
	v_pk_fma_f32 v[158:159], v[124:125], v[42:43], v[158:159]
	s_nop 0
	v_pk_fma_f32 v[158:159], v[122:123], v[44:45], v[158:159]
	s_nop 0
	v_pk_fma_f32 v[158:159], v[120:121], v[46:47], v[158:159]
	s_nop 0
	v_add_f32_e32 v158, v158, v159
	s_mov_b32 s6, 0x80808080
	s_mov_b32 s7, 0x80808080
	v_add_f32_dpp v158, v158, v158 quad_perm:[1,0,3,2] row_mask:0xf bank_mask:0xf bound_ctrl:1
	s_nop 1
	v_add_f32_dpp v158, v158, v158 quad_perm:[2,3,0,1] row_mask:0xf bank_mask:0xf bound_ctrl:1
	s_nop 1
	v_add_f32_dpp v158, v158, v158 row_half_mirror row_mask:0xf bank_mask:0xf bound_ctrl:1
	v_pk_mul_f32 v[126:127], v[48:49], v[126:127]
	v_pk_mul_f32 v[124:125], v[50:51], v[124:125]
	v_pk_mul_f32 v[122:123], v[52:53], v[122:123]
	v_pk_mul_f32 v[120:121], v[54:55], v[120:121]
	v_cndmask_b32_e64 v94, v94, v158, s[6:7]
	ds_read_b128 v[40:43], v154 offset:26112
	ds_read_b128 v[44:47], v154 offset:26128
	ds_read_b128 v[64:67], v154 offset:26880
	ds_read_b128 v[68:71], v154 offset:26896
	ds_read_b128 v[56:59], v154 offset:26624
	ds_read_b128 v[60:63], v154 offset:26640
	ds_read_b128 v[72:75], v154 offset:27136
	ds_read_b128 v[76:79], v154 offset:27152
	ds_read_b32 v128, v153 offset:27392
	s_waitcnt lgkmcnt(9)
; #define LAS __attribute__((address_space(3)))
; DI unsigned pack2(float lo, float hi) { f32x2 v = {lo, hi}; return __builtin_bit_cast(unsigned, __builtin_convertvector(v, bf16x2_t)); }
; DI void scan_item(PP p, int l, int item, LAS unsigned char* lds) {
;     ...
;     for (int c = 0; c < NCH; ++c) {
;         if (wid >= 4) { if (c + 1 < NCH) { fill(c + 1); if (c + 2 < NCH) gl(c + 2); } }
;         else {
;             const LAS float* sp = buf + ((c & 1) * T) * 384;
;             f32x4 Ar0, Ar1, Aw0, Aw1, Ak0, Ak1, Aa0, Aa1, Ab0, Ab1; float Avv;
;             f32x4 Br0, Br1, Bw0, Bw1, Bk0, Bk1, Ba0, Ba1, Bb0, Bb1; float Bvv;
;             SC_LD(A, sp);
;             const ptrdiff_t ystep = dir ? -512 : 512;
;             u16* Yl = Yp + (size_t)steprow(b, dir, c * T) * 512 + (ptrdiff_t)ks * ystep;
; #pragma nounroll
;             for (int st = 0; st < T; st += 2) {
;                 SC_LD(B, sp + (st + 1) * 384);
;                 SC_STEP(A, st);
;                 if (st + 2 < T) SC_LD(A, sp + (st + 2) * 384);
;                 SC_STEP(B, st + 1);
;                 if ((st & 6) == 6) {
;                     const LAS float* rp = ypl + (ks * 68 - lane) + (lane & ~7);
;                     const f32x4 q0 = *(const LAS f32x4*)rp, q1 = *(const LAS f32x4*)(rp + 4);
;                     Yl[(ptrdiff_t)(st - 6) * ystep] = (u16)(pack2(((q0[0] + q0[1]) + (q0[2] + q0[3])) + ((q1[0] + q1[1]) + (q1[2] + q1[3])), 0.f) & 0xffffu);
;                 }
;             }
	v_pk_mul_f32 v[156:157], v[24:25], v[126:127]
	v_pk_mul_f32 v[90:91], v[28:29], v[122:123]
	v_pk_fma_f32 v[126:127], v[116:117], v[16:17], v[126:127] op_sel_hi:[0,1,1]
	v_pk_fma_f32 v[156:157], v[124:125], v[26:27], v[156:157]
	v_pk_fma_f32 v[90:91], v[120:121], v[30:31], v[90:91]
	v_pk_fma_f32 v[124:125], v[116:117], v[18:19], v[124:125] op_sel_hi:[0,1,1]
	v_pk_fma_f32 v[122:123], v[116:117], v[20:21], v[122:123] op_sel_hi:[0,1,1]
	v_pk_add_f32 v[156:157], v[156:157], v[90:91]
	v_pk_fma_f32 v[120:121], v[116:117], v[22:23], v[120:121] op_sel_hi:[0,1,1]
	v_add_f32_e32 v155, v156, v157
	s_nop 1
	v_add_f32_dpp v155, v155, v155 quad_perm:[1,0,3,2] row_mask:0xf bank_mask:0xf bound_ctrl:1
	s_nop 1
	v_add_f32_dpp v155, v155, v155 quad_perm:[2,3,0,1] row_mask:0xf bank_mask:0xf bound_ctrl:1
	s_nop 1
	v_add_f32_dpp v156, v155, v155 row_half_mirror row_mask:0xf bank_mask:0xf bound_ctrl:1
	v_pk_fma_f32 v[126:127], v[156:157], v[32:33], v[126:127] op_sel_hi:[0,1,1]
	v_pk_fma_f32 v[124:125], v[156:157], v[34:35], v[124:125] op_sel_hi:[0,1,1]
	v_pk_fma_f32 v[122:123], v[156:157], v[36:37], v[122:123] op_sel_hi:[0,1,1]
	v_pk_fma_f32 v[120:121], v[156:157], v[38:39], v[120:121] op_sel_hi:[0,1,1]
	v_cvt_pk_bf16_f32 v82, v94, v94
	global_store_short v[118:119], v82, off
	v_lshl_add_u64 v[118:119], s[8:9], 0, v[118:119]
	ds_read_b128 v[24:27], v154 offset:28416
	ds_read_b128 v[28:31], v154 offset:28432
	ds_read_b128 v[16:19], v154 offset:28160
	ds_read_b128 v[20:23], v154 offset:28176
	ds_read_b128 v[32:35], v154 offset:28672
	ds_read_b128 v[36:39], v154 offset:28688
	ds_read_b32 v116, v153 offset:28928
	s_waitcnt lgkmcnt(7)
	v_pk_mul_f32 v[156:157], v[64:65], v[126:127]
	v_pk_mul_f32 v[90:91], v[68:69], v[122:123]
	v_pk_mul_f32 v[158:159], v[0:1], v[126:127]
	v_pk_fma_f32 v[156:157], v[124:125], v[66:67], v[156:157]
	v_pk_fma_f32 v[90:91], v[120:121], v[70:71], v[90:91]
	v_pk_fma_f32 v[158:159], v[124:125], v[2:3], v[158:159]
	v_pk_fma_f32 v[126:127], v[128:129], v[56:57], v[126:127] op_sel_hi:[0,1,1]
	v_pk_fma_f32 v[158:159], v[122:123], v[4:5], v[158:159]
	v_pk_fma_f32 v[124:125], v[128:129], v[58:59], v[124:125] op_sel_hi:[0,1,1]
	v_pk_add_f32 v[156:157], v[156:157], v[90:91]
	v_pk_fma_f32 v[158:159], v[120:121], v[6:7], v[158:159]
	v_add_f32_e32 v155, v156, v157
	v_pk_fma_f32 v[122:123], v[128:129], v[60:61], v[122:123] op_sel_hi:[0,1,1]
	v_pk_fma_f32 v[120:121], v[128:129], v[62:63], v[120:121] op_sel_hi:[0,1,1]
	ds_read_b128 v[0:3], v154 offset:27648
	ds_read_b128 v[4:7], v154 offset:27664
	v_add_f32_e32 v158, v158, v159
	v_add_f32_dpp v155, v155, v155 quad_perm:[1,0,3,2] row_mask:0xf bank_mask:0xf bound_ctrl:1
	s_mov_b32 s6, 0x1010101
	s_mov_b32 s7, 0x1010101
	v_add_f32_dpp v158, v158, v158 quad_perm:[1,0,3,2] row_mask:0xf bank_mask:0xf bound_ctrl:1
	v_add_f32_dpp v155, v155, v155 quad_perm:[2,3,0,1] row_mask:0xf bank_mask:0xf bound_ctrl:1
	s_nop 0
	v_add_f32_dpp v158, v158, v158 quad_perm:[2,3,0,1] row_mask:0xf bank_mask:0xf bound_ctrl:1
	v_add_f32_dpp v156, v155, v155 row_half_mirror row_mask:0xf bank_mask:0xf bound_ctrl:1
	v_pk_fma_f32 v[126:127], v[156:157], v[72:73], v[126:127] op_sel_hi:[0,1,1]
	v_pk_fma_f32 v[124:125], v[156:157], v[74:75], v[124:125] op_sel_hi:[0,1,1]
	v_add_f32_dpp v158, v158, v158 row_half_mirror row_mask:0xf bank_mask:0xf bound_ctrl:1
	v_pk_fma_f32 v[122:123], v[156:157], v[76:77], v[122:123] op_sel_hi:[0,1,1]
	v_pk_fma_f32 v[120:121], v[156:157], v[78:79], v[120:121] op_sel_hi:[0,1,1]
	v_cndmask_b32_e64 v94, v94, v158, s[6:7]
	ds_read_b128 v[64:67], v154 offset:29952
	ds_read_b128 v[68:71], v154 offset:29968
	ds_read_b128 v[56:59], v154 offset:29696
	ds_read_b128 v[60:63], v154 offset:29712
	ds_read_b128 v[72:75], v154 offset:30208
	ds_read_b128 v[76:79], v154 offset:30224
	ds_read_b32 v128, v153 offset:30464
	s_waitcnt lgkmcnt(7)
	v_pk_mul_f32 v[156:157], v[24:25], v[126:127]
	v_pk_mul_f32 v[90:91], v[28:29], v[122:123]
	v_pk_mul_f32 v[158:159], v[40:41], v[126:127]
	v_pk_fma_f32 v[156:157], v[124:125], v[26:27], v[156:157]
	v_pk_fma_f32 v[90:91], v[120:121], v[30:31], v[90:91]
	v_pk_fma_f32 v[158:159], v[124:125], v[42:43], v[158:159]
	v_pk_fma_f32 v[126:127], v[116:117], v[16:17], v[126:127] op_sel_hi:[0,1,1]
	v_pk_fma_f32 v[158:159], v[122:123], v[44:45], v[158:159]
	v_pk_fma_f32 v[124:125], v[116:117], v[18:19], v[124:125] op_sel_hi:[0,1,1]
	v_pk_add_f32 v[156:157], v[156:157], v[90:91]
	v_pk_fma_f32 v[158:159], v[120:121], v[46:47], v[158:159]
	v_add_f32_e32 v155, v156, v157
	v_pk_fma_f32 v[122:123], v[116:117], v[20:21], v[122:123] op_sel_hi:[0,1,1]
	v_pk_fma_f32 v[120:121], v[116:117], v[22:23], v[120:121] op_sel_hi:[0,1,1]
	ds_read_b128 v[40:43], v154 offset:29184
	ds_read_b128 v[44:47], v154 offset:29200
	v_add_f32_e32 v158, v158, v159
	v_add_f32_dpp v155, v155, v155 quad_perm:[1,0,3,2] row_mask:0xf bank_mask:0xf bound_ctrl:1
	s_mov_b32 s6, 0x2020202
	s_mov_b32 s7, 0x2020202
	v_add_f32_dpp v158, v158, v158 quad_perm:[1,0,3,2] row_mask:0xf bank_mask:0xf bound_ctrl:1
	v_add_f32_dpp v155, v155, v155 quad_perm:[2,3,0,1] row_mask:0xf bank_mask:0xf bound_ctrl:1
	s_nop 0
	v_add_f32_dpp v158, v158, v158 quad_perm:[2,3,0,1] row_mask:0xf bank_mask:0xf bound_ctrl:1
	v_add_f32_dpp v156, v155, v155 row_half_mirror row_mask:0xf bank_mask:0xf bound_ctrl:1
	v_pk_fma_f32 v[126:127], v[156:157], v[32:33], v[126:127] op_sel_hi:[0,1,1]
	v_pk_fma_f32 v[124:125], v[156:157], v[34:35], v[124:125] op_sel_hi:[0,1,1]
	v_add_f32_dpp v158, v158, v158 row_half_mirror row_mask:0xf bank_mask:0xf bound_ctrl:1
	v_pk_fma_f32 v[122:123], v[156:157], v[36:37], v[122:123] op_sel_hi:[0,1,1]
	v_pk_fma_f32 v[120:121], v[156:157], v[38:39], v[120:121] op_sel_hi:[0,1,1]
	v_cndmask_b32_e64 v94, v94, v158, s[6:7]
	ds_read_b128 v[24:27], v154 offset:31488
	ds_read_b128 v[28:31], v154 offset:31504
	ds_read_b128 v[16:19], v154 offset:31232
	ds_read_b128 v[20:23], v154 offset:31248
	ds_read_b128 v[32:35], v154 offset:31744
	ds_read_b128 v[36:39], v154 offset:31760
	ds_read_b32 v116, v153 offset:32000
	s_waitcnt lgkmcnt(7)
; #define LAS __attribute__((address_space(3)))
; DI unsigned pack2(float lo, float hi) { f32x2 v = {lo, hi}; return __builtin_bit_cast(unsigned, __builtin_convertvector(v, bf16x2_t)); }
; DI void scan_item(PP p, int l, int item, LAS unsigned char* lds) {
;     ...
;     for (int c = 0; c < NCH; ++c) {
;         if (wid >= 4) { if (c + 1 < NCH) { fill(c + 1); if (c + 2 < NCH) gl(c + 2); } }
;         else {
;             const LAS float* sp = buf + ((c & 1) * T) * 384;
;             f32x4 Ar0, Ar1, Aw0, Aw1, Ak0, Ak1, Aa0, Aa1, Ab0, Ab1; float Avv;
;             f32x4 Br0, Br1, Bw0, Bw1, Bk0, Bk1, Ba0, Ba1, Bb0, Bb1; float Bvv;
;             SC_LD(A, sp);
;             const ptrdiff_t ystep = dir ? -512 : 512;
;             u16* Yl = Yp + (size_t)steprow(b, dir, c * T) * 512 + (ptrdiff_t)ks * ystep;
; #pragma nounroll
;             for (int st = 0; st < T; st += 2) {
;                 SC_LD(B, sp + (st + 1) * 384);
;                 SC_STEP(A, st);
;                 if (st + 2 < T) SC_LD(A, sp + (st + 2) * 384);
;                 SC_STEP(B, st + 1);
;                 if ((st & 6) == 6) {
;                     const LAS float* rp = ypl + (ks * 68 - lane) + (lane & ~7);
;                     const f32x4 q0 = *(const LAS f32x4*)rp, q1 = *(const LAS f32x4*)(rp + 4);
;                     Yl[(ptrdiff_t)(st - 6) * ystep] = (u16)(pack2(((q0[0] + q0[1]) + (q0[2] + q0[3])) + ((q1[0] + q1[1]) + (q1[2] + q1[3])), 0.f) & 0xffffu);
;                 }
;             }
	v_pk_mul_f32 v[156:157], v[64:65], v[126:127]
	v_pk_mul_f32 v[90:91], v[68:69], v[122:123]
	v_pk_mul_f32 v[158:159], v[0:1], v[126:127]
	v_pk_fma_f32 v[156:157], v[124:125], v[66:67], v[156:157]
	v_pk_fma_f32 v[90:91], v[120:121], v[70:71], v[90:91]
	v_pk_fma_f32 v[158:159], v[124:125], v[2:3], v[158:159]
	v_pk_fma_f32 v[126:127], v[128:129], v[56:57], v[126:127] op_sel_hi:[0,1,1]
	v_pk_fma_f32 v[158:159], v[122:123], v[4:5], v[158:159]
	v_pk_fma_f32 v[124:125], v[128:129], v[58:59], v[124:125] op_sel_hi:[0,1,1]
	v_pk_add_f32 v[156:157], v[156:157], v[90:91]
	v_pk_fma_f32 v[158:159], v[120:121], v[6:7], v[158:159]
	v_add_f32_e32 v155, v156, v157
	v_pk_fma_f32 v[122:123], v[128:129], v[60:61], v[122:123] op_sel_hi:[0,1,1]
	v_pk_fma_f32 v[120:121], v[128:129], v[62:63], v[120:121] op_sel_hi:[0,1,1]
	ds_read_b128 v[0:3], v154 offset:30720
	ds_read_b128 v[4:7], v154 offset:30736
	v_add_f32_e32 v158, v158, v159
	v_add_f32_dpp v155, v155, v155 quad_perm:[1,0,3,2] row_mask:0xf bank_mask:0xf bound_ctrl:1
	s_mov_b32 s6, 0x4040404
	s_mov_b32 s7, 0x4040404
	v_add_f32_dpp v158, v158, v158 quad_perm:[1,0,3,2] row_mask:0xf bank_mask:0xf bound_ctrl:1
	v_add_f32_dpp v155, v155, v155 quad_perm:[2,3,0,1] row_mask:0xf bank_mask:0xf bound_ctrl:1
	s_nop 0
	v_add_f32_dpp v158, v158, v158 quad_perm:[2,3,0,1] row_mask:0xf bank_mask:0xf bound_ctrl:1
	v_add_f32_dpp v156, v155, v155 row_half_mirror row_mask:0xf bank_mask:0xf bound_ctrl:1
	v_pk_fma_f32 v[126:127], v[156:157], v[72:73], v[126:127] op_sel_hi:[0,1,1]
	v_pk_fma_f32 v[124:125], v[156:157], v[74:75], v[124:125] op_sel_hi:[0,1,1]
	v_add_f32_dpp v158, v158, v158 row_half_mirror row_mask:0xf bank_mask:0xf bound_ctrl:1
	v_pk_fma_f32 v[122:123], v[156:157], v[76:77], v[122:123] op_sel_hi:[0,1,1]
	v_pk_fma_f32 v[120:121], v[156:157], v[78:79], v[120:121] op_sel_hi:[0,1,1]
	v_cndmask_b32_e64 v94, v94, v158, s[6:7]
	ds_read_b128 v[64:67], v154 offset:33024
	ds_read_b128 v[68:71], v154 offset:33040
	ds_read_b128 v[56:59], v154 offset:32768
	ds_read_b128 v[60:63], v154 offset:32784
	ds_read_b128 v[72:75], v154 offset:33280
	ds_read_b128 v[76:79], v154 offset:33296
	ds_read_b32 v128, v153 offset:33536
	s_waitcnt lgkmcnt(7)
	v_pk_mul_f32 v[156:157], v[24:25], v[126:127]
	v_pk_mul_f32 v[90:91], v[28:29], v[122:123]
	v_pk_mul_f32 v[158:159], v[40:41], v[126:127]
	v_pk_fma_f32 v[156:157], v[124:125], v[26:27], v[156:157]
	v_pk_fma_f32 v[90:91], v[120:121], v[30:31], v[90:91]
	v_pk_fma_f32 v[158:159], v[124:125], v[42:43], v[158:159]
	v_pk_fma_f32 v[126:127], v[116:117], v[16:17], v[126:127] op_sel_hi:[0,1,1]
	v_pk_fma_f32 v[158:159], v[122:123], v[44:45], v[158:159]
	v_pk_fma_f32 v[124:125], v[116:117], v[18:19], v[124:125] op_sel_hi:[0,1,1]
	v_pk_add_f32 v[156:157], v[156:157], v[90:91]
	v_pk_fma_f32 v[158:159], v[120:121], v[46:47], v[158:159]
	v_add_f32_e32 v155, v156, v157
	v_pk_fma_f32 v[122:123], v[116:117], v[20:21], v[122:123] op_sel_hi:[0,1,1]
	v_pk_fma_f32 v[120:121], v[116:117], v[22:23], v[120:121] op_sel_hi:[0,1,1]
	ds_read_b128 v[40:43], v154 offset:32256
	ds_read_b128 v[44:47], v154 offset:32272
	v_add_f32_e32 v158, v158, v159
	v_add_f32_dpp v155, v155, v155 quad_perm:[1,0,3,2] row_mask:0xf bank_mask:0xf bound_ctrl:1
	s_mov_b32 s6, 0x8080808
	s_mov_b32 s7, 0x8080808
	v_add_f32_dpp v158, v158, v158 quad_perm:[1,0,3,2] row_mask:0xf bank_mask:0xf bound_ctrl:1
	v_add_f32_dpp v155, v155, v155 quad_perm:[2,3,0,1] row_mask:0xf bank_mask:0xf bound_ctrl:1
	s_nop 0
	v_add_f32_dpp v158, v158, v158 quad_perm:[2,3,0,1] row_mask:0xf bank_mask:0xf bound_ctrl:1
	v_add_f32_dpp v156, v155, v155 row_half_mirror row_mask:0xf bank_mask:0xf bound_ctrl:1
	v_pk_fma_f32 v[126:127], v[156:157], v[32:33], v[126:127] op_sel_hi:[0,1,1]
	v_pk_fma_f32 v[124:125], v[156:157], v[34:35], v[124:125] op_sel_hi:[0,1,1]
	v_add_f32_dpp v158, v158, v158 row_half_mirror row_mask:0xf bank_mask:0xf bound_ctrl:1
	v_pk_fma_f32 v[122:123], v[156:157], v[36:37], v[122:123] op_sel_hi:[0,1,1]
	v_pk_fma_f32 v[120:121], v[156:157], v[38:39], v[120:121] op_sel_hi:[0,1,1]
	v_cndmask_b32_e64 v94, v94, v158, s[6:7]
	ds_read_b128 v[24:27], v154 offset:34560
	ds_read_b128 v[28:31], v154 offset:34576
	ds_read_b128 v[16:19], v154 offset:34304
	ds_read_b128 v[20:23], v154 offset:34320
	ds_read_b128 v[32:35], v154 offset:34816
	ds_read_b128 v[36:39], v154 offset:34832
	ds_read_b32 v116, v153 offset:35072
	s_waitcnt lgkmcnt(7)
	v_pk_mul_f32 v[156:157], v[64:65], v[126:127]
	v_pk_mul_f32 v[90:91], v[68:69], v[122:123]
	v_pk_mul_f32 v[158:159], v[0:1], v[126:127]
	v_pk_fma_f32 v[156:157], v[124:125], v[66:67], v[156:157]
	v_pk_fma_f32 v[90:91], v[120:121], v[70:71], v[90:91]
	v_pk_fma_f32 v[158:159], v[124:125], v[2:3], v[158:159]
	v_pk_fma_f32 v[126:127], v[128:129], v[56:57], v[126:127] op_sel_hi:[0,1,1]
	v_pk_fma_f32 v[158:159], v[122:123], v[4:5], v[158:159]
	v_pk_fma_f32 v[124:125], v[128:129], v[58:59], v[124:125] op_sel_hi:[0,1,1]
	v_pk_add_f32 v[156:157], v[156:157], v[90:91]
	v_pk_fma_f32 v[158:159], v[120:121], v[6:7], v[158:159]
	v_add_f32_e32 v155, v156, v157
	v_pk_fma_f32 v[122:123], v[128:129], v[60:61], v[122:123] op_sel_hi:[0,1,1]
	v_pk_fma_f32 v[120:121], v[128:129], v[62:63], v[120:121] op_sel_hi:[0,1,1]
	ds_read_b128 v[0:3], v154 offset:33792
	ds_read_b128 v[4:7], v154 offset:33808
	v_add_f32_e32 v158, v158, v159
	v_add_f32_dpp v155, v155, v155 quad_perm:[1,0,3,2] row_mask:0xf bank_mask:0xf bound_ctrl:1
	s_mov_b32 s6, 0x10101010
	s_mov_b32 s7, 0x10101010
	v_add_f32_dpp v158, v158, v158 quad_perm:[1,0,3,2] row_mask:0xf bank_mask:0xf bound_ctrl:1
	v_add_f32_dpp v155, v155, v155 quad_perm:[2,3,0,1] row_mask:0xf bank_mask:0xf bound_ctrl:1
	s_nop 0
	v_add_f32_dpp v158, v158, v158 quad_perm:[2,3,0,1] row_mask:0xf bank_mask:0xf bound_ctrl:1
	v_add_f32_dpp v156, v155, v155 row_half_mirror row_mask:0xf bank_mask:0xf bound_ctrl:1
	v_pk_fma_f32 v[126:127], v[156:157], v[72:73], v[126:127] op_sel_hi:[0,1,1]
	v_pk_fma_f32 v[124:125], v[156:157], v[74:75], v[124:125] op_sel_hi:[0,1,1]
	v_add_f32_dpp v158, v158, v158 row_half_mirror row_mask:0xf bank_mask:0xf bound_ctrl:1
	v_pk_fma_f32 v[122:123], v[156:157], v[76:77], v[122:123] op_sel_hi:[0,1,1]
	v_pk_fma_f32 v[120:121], v[156:157], v[78:79], v[120:121] op_sel_hi:[0,1,1]
	v_cndmask_b32_e64 v94, v94, v158, s[6:7]
	ds_read_b128 v[64:67], v154 offset:36096
	ds_read_b128 v[68:71], v154 offset:36112
	ds_read_b128 v[56:59], v154 offset:35840
	ds_read_b128 v[60:63], v154 offset:35856
	ds_read_b128 v[72:75], v154 offset:36352
	ds_read_b128 v[76:79], v154 offset:36368
	ds_read_b32 v128, v153 offset:36608
	ds_read_b128 v[48:51], v154 offset:35584
	ds_read_b128 v[52:55], v154 offset:35600
	s_waitcnt lgkmcnt(9)
; #define LAS __attribute__((address_space(3)))
; DI unsigned pack2(float lo, float hi) { f32x2 v = {lo, hi}; return __builtin_bit_cast(unsigned, __builtin_convertvector(v, bf16x2_t)); }
; DI void scan_item(PP p, int l, int item, LAS unsigned char* lds) {
;     ...
;     for (int c = 0; c < NCH; ++c) {
;         if (wid >= 4) { if (c + 1 < NCH) { fill(c + 1); if (c + 2 < NCH) gl(c + 2); } }
;         else {
;             const LAS float* sp = buf + ((c & 1) * T) * 384;
;             f32x4 Ar0, Ar1, Aw0, Aw1, Ak0, Ak1, Aa0, Aa1, Ab0, Ab1; float Avv;
;             f32x4 Br0, Br1, Bw0, Bw1, Bk0, Bk1, Ba0, Ba1, Bb0, Bb1; float Bvv;
;             SC_LD(A, sp);
;             const ptrdiff_t ystep = dir ? -512 : 512;
;             u16* Yl = Yp + (size_t)steprow(b, dir, c * T) * 512 + (ptrdiff_t)ks * ystep;
; #pragma nounroll
;             for (int st = 0; st < T; st += 2) {
;                 SC_LD(B, sp + (st + 1) * 384);
;                 SC_STEP(A, st);
;                 if (st + 2 < T) SC_LD(A, sp + (st + 2) * 384);
;                 SC_STEP(B, st + 1);
;                 if ((st & 6) == 6) {
;                     const LAS float* rp = ypl + (ks * 68 - lane) + (lane & ~7);
;                     const f32x4 q0 = *(const LAS f32x4*)rp, q1 = *(const LAS f32x4*)(rp + 4);
;                     Yl[(ptrdiff_t)(st - 6) * ystep] = (u16)(pack2(((q0[0] + q0[1]) + (q0[2] + q0[3])) + ((q1[0] + q1[1]) + (q1[2] + q1[3])), 0.f) & 0xffffu);
;                 }
;             }
	v_pk_mul_f32 v[156:157], v[24:25], v[126:127]
	v_pk_mul_f32 v[90:91], v[28:29], v[122:123]
	v_pk_mul_f32 v[158:159], v[40:41], v[126:127]
	v_pk_fma_f32 v[156:157], v[124:125], v[26:27], v[156:157]
	v_pk_fma_f32 v[90:91], v[120:121], v[30:31], v[90:91]
	v_pk_fma_f32 v[158:159], v[124:125], v[42:43], v[158:159]
	v_pk_fma_f32 v[126:127], v[116:117], v[16:17], v[126:127] op_sel_hi:[0,1,1]
	v_pk_fma_f32 v[158:159], v[122:123], v[44:45], v[158:159]
	v_pk_fma_f32 v[124:125], v[116:117], v[18:19], v[124:125] op_sel_hi:[0,1,1]
	v_pk_add_f32 v[156:157], v[156:157], v[90:91]
	v_pk_fma_f32 v[158:159], v[120:121], v[46:47], v[158:159]
	v_add_f32_e32 v155, v156, v157
	v_pk_fma_f32 v[122:123], v[116:117], v[20:21], v[122:123] op_sel_hi:[0,1,1]
	v_pk_fma_f32 v[120:121], v[116:117], v[22:23], v[120:121] op_sel_hi:[0,1,1]
	ds_read_b128 v[40:43], v154 offset:35328
	ds_read_b128 v[44:47], v154 offset:35344
	v_add_f32_e32 v158, v158, v159
	v_add_f32_dpp v155, v155, v155 quad_perm:[1,0,3,2] row_mask:0xf bank_mask:0xf bound_ctrl:1
	s_mov_b32 s6, 0x20202020
	s_mov_b32 s7, 0x20202020
	v_add_f32_dpp v158, v158, v158 quad_perm:[1,0,3,2] row_mask:0xf bank_mask:0xf bound_ctrl:1
	v_add_f32_dpp v155, v155, v155 quad_perm:[2,3,0,1] row_mask:0xf bank_mask:0xf bound_ctrl:1
	s_nop 0
	v_add_f32_dpp v158, v158, v158 quad_perm:[2,3,0,1] row_mask:0xf bank_mask:0xf bound_ctrl:1
	v_add_f32_dpp v156, v155, v155 row_half_mirror row_mask:0xf bank_mask:0xf bound_ctrl:1
	v_pk_fma_f32 v[126:127], v[156:157], v[32:33], v[126:127] op_sel_hi:[0,1,1]
	v_pk_fma_f32 v[124:125], v[156:157], v[34:35], v[124:125] op_sel_hi:[0,1,1]
	v_add_f32_dpp v158, v158, v158 row_half_mirror row_mask:0xf bank_mask:0xf bound_ctrl:1
	v_pk_fma_f32 v[122:123], v[156:157], v[36:37], v[122:123] op_sel_hi:[0,1,1]
	v_pk_fma_f32 v[120:121], v[156:157], v[38:39], v[120:121] op_sel_hi:[0,1,1]
	v_cndmask_b32_e64 v94, v94, v158, s[6:7]
	ds_read_b128 v[24:27], v154 offset:37632
	ds_read_b128 v[28:31], v154 offset:37648
	ds_read_b128 v[16:19], v154 offset:37376
	ds_read_b128 v[20:23], v154 offset:37392
	ds_read_b128 v[32:35], v154 offset:37888
	ds_read_b128 v[36:39], v154 offset:37904
	ds_read_b32 v116, v153 offset:38144
	s_waitcnt lgkmcnt(7)
	v_pk_mul_f32 v[156:157], v[64:65], v[126:127]
	v_pk_mul_f32 v[90:91], v[68:69], v[122:123]
	v_pk_mul_f32 v[158:159], v[0:1], v[126:127]
	v_pk_fma_f32 v[156:157], v[124:125], v[66:67], v[156:157]
	v_pk_fma_f32 v[90:91], v[120:121], v[70:71], v[90:91]
	v_pk_fma_f32 v[158:159], v[124:125], v[2:3], v[158:159]
	v_pk_fma_f32 v[126:127], v[128:129], v[56:57], v[126:127] op_sel_hi:[0,1,1]
	v_pk_fma_f32 v[158:159], v[122:123], v[4:5], v[158:159]
	v_pk_fma_f32 v[124:125], v[128:129], v[58:59], v[124:125] op_sel_hi:[0,1,1]
	v_pk_add_f32 v[156:157], v[156:157], v[90:91]
	v_pk_fma_f32 v[158:159], v[120:121], v[6:7], v[158:159]
	v_add_f32_e32 v155, v156, v157
	v_pk_fma_f32 v[122:123], v[128:129], v[60:61], v[122:123] op_sel_hi:[0,1,1]
	v_pk_fma_f32 v[120:121], v[128:129], v[62:63], v[120:121] op_sel_hi:[0,1,1]
	ds_read_b128 v[0:3], v154 offset:36864
	ds_read_b128 v[4:7], v154 offset:36880
	v_add_f32_e32 v158, v158, v159
	v_add_f32_dpp v155, v155, v155 quad_perm:[1,0,3,2] row_mask:0xf bank_mask:0xf bound_ctrl:1
	s_mov_b32 s6, 0x40404040
	s_mov_b32 s7, 0x40404040
	v_add_f32_dpp v158, v158, v158 quad_perm:[1,0,3,2] row_mask:0xf bank_mask:0xf bound_ctrl:1
	v_add_f32_dpp v155, v155, v155 quad_perm:[2,3,0,1] row_mask:0xf bank_mask:0xf bound_ctrl:1
	s_nop 0
	v_add_f32_dpp v158, v158, v158 quad_perm:[2,3,0,1] row_mask:0xf bank_mask:0xf bound_ctrl:1
	v_add_f32_dpp v156, v155, v155 row_half_mirror row_mask:0xf bank_mask:0xf bound_ctrl:1
	v_pk_fma_f32 v[126:127], v[156:157], v[72:73], v[126:127] op_sel_hi:[0,1,1]
	v_pk_fma_f32 v[124:125], v[156:157], v[74:75], v[124:125] op_sel_hi:[0,1,1]
	v_add_f32_dpp v158, v158, v158 row_half_mirror row_mask:0xf bank_mask:0xf bound_ctrl:1
	v_pk_fma_f32 v[122:123], v[156:157], v[76:77], v[122:123] op_sel_hi:[0,1,1]
	v_pk_fma_f32 v[120:121], v[156:157], v[78:79], v[120:121] op_sel_hi:[0,1,1]
	v_cndmask_b32_e64 v94, v94, v158, s[6:7]
	v_pk_mul_f32 v[158:159], v[40:41], v[126:127]
	s_nop 0
	v_pk_fma_f32 v[158:159], v[124:125], v[42:43], v[158:159]
	s_nop 0
	v_pk_fma_f32 v[158:159], v[122:123], v[44:45], v[158:159]
	s_nop 0
	v_pk_fma_f32 v[158:159], v[120:121], v[46:47], v[158:159]
	s_nop 0
	v_add_f32_e32 v158, v158, v159
	s_mov_b32 s6, 0x80808080
	s_mov_b32 s7, 0x80808080
	v_add_f32_dpp v158, v158, v158 quad_perm:[1,0,3,2] row_mask:0xf bank_mask:0xf bound_ctrl:1
	s_nop 1
	v_add_f32_dpp v158, v158, v158 quad_perm:[2,3,0,1] row_mask:0xf bank_mask:0xf bound_ctrl:1
	s_nop 1
	v_add_f32_dpp v158, v158, v158 row_half_mirror row_mask:0xf bank_mask:0xf bound_ctrl:1
	v_pk_mul_f32 v[126:127], v[48:49], v[126:127]
	v_pk_mul_f32 v[124:125], v[50:51], v[124:125]
	v_pk_mul_f32 v[122:123], v[52:53], v[122:123]
	v_pk_mul_f32 v[120:121], v[54:55], v[120:121]
	v_cndmask_b32_e64 v94, v94, v158, s[6:7]
	ds_read_b128 v[40:43], v154 offset:38400
	ds_read_b128 v[44:47], v154 offset:38416
	ds_read_b128 v[64:67], v154 offset:39168
	ds_read_b128 v[68:71], v154 offset:39184
	ds_read_b128 v[56:59], v154 offset:38912
	ds_read_b128 v[60:63], v154 offset:38928
	ds_read_b128 v[72:75], v154 offset:39424
	ds_read_b128 v[76:79], v154 offset:39440
	ds_read_b32 v128, v153 offset:39680
	s_waitcnt lgkmcnt(9)
; #define LAS __attribute__((address_space(3)))
; DI unsigned pack2(float lo, float hi) { f32x2 v = {lo, hi}; return __builtin_bit_cast(unsigned, __builtin_convertvector(v, bf16x2_t)); }
; DI void scan_item(PP p, int l, int item, LAS unsigned char* lds) {
;     ...
;     for (int c = 0; c < NCH; ++c) {
;         if (wid >= 4) { if (c + 1 < NCH) { fill(c + 1); if (c + 2 < NCH) gl(c + 2); } }
;         else {
;             const LAS float* sp = buf + ((c & 1) * T) * 384;
;             f32x4 Ar0, Ar1, Aw0, Aw1, Ak0, Ak1, Aa0, Aa1, Ab0, Ab1; float Avv;
;             f32x4 Br0, Br1, Bw0, Bw1, Bk0, Bk1, Ba0, Ba1, Bb0, Bb1; float Bvv;
;             SC_LD(A, sp);
;             const ptrdiff_t ystep = dir ? -512 : 512;
;             u16* Yl = Yp + (size_t)steprow(b, dir, c * T) * 512 + (ptrdiff_t)ks * ystep;
; #pragma nounroll
;             for (int st = 0; st < T; st += 2) {
;                 SC_LD(B, sp + (st + 1) * 384);
;                 SC_STEP(A, st);
;                 if (st + 2 < T) SC_LD(A, sp + (st + 2) * 384);
;                 SC_STEP(B, st + 1);
;                 if ((st & 6) == 6) {
;                     const LAS float* rp = ypl + (ks * 68 - lane) + (lane & ~7);
;                     const f32x4 q0 = *(const LAS f32x4*)rp, q1 = *(const LAS f32x4*)(rp + 4);
;                     Yl[(ptrdiff_t)(st - 6) * ystep] = (u16)(pack2(((q0[0] + q0[1]) + (q0[2] + q0[3])) + ((q1[0] + q1[1]) + (q1[2] + q1[3])), 0.f) & 0xffffu);
;                 }
;             }
	v_pk_mul_f32 v[156:157], v[24:25], v[126:127]
	v_pk_mul_f32 v[90:91], v[28:29], v[122:123]
	v_pk_fma_f32 v[126:127], v[116:117], v[16:17], v[126:127] op_sel_hi:[0,1,1]
	v_pk_fma_f32 v[156:157], v[124:125], v[26:27], v[156:157]
	v_pk_fma_f32 v[90:91], v[120:121], v[30:31], v[90:91]
	v_pk_fma_f32 v[124:125], v[116:117], v[18:19], v[124:125] op_sel_hi:[0,1,1]
	v_pk_fma_f32 v[122:123], v[116:117], v[20:21], v[122:123] op_sel_hi:[0,1,1]
	v_pk_add_f32 v[156:157], v[156:157], v[90:91]
	v_pk_fma_f32 v[120:121], v[116:117], v[22:23], v[120:121] op_sel_hi:[0,1,1]
	v_add_f32_e32 v155, v156, v157
	s_nop 1
	v_add_f32_dpp v155, v155, v155 quad_perm:[1,0,3,2] row_mask:0xf bank_mask:0xf bound_ctrl:1
	s_nop 1
	v_add_f32_dpp v155, v155, v155 quad_perm:[2,3,0,1] row_mask:0xf bank_mask:0xf bound_ctrl:1
	s_nop 1
	v_add_f32_dpp v156, v155, v155 row_half_mirror row_mask:0xf bank_mask:0xf bound_ctrl:1
	v_pk_fma_f32 v[126:127], v[156:157], v[32:33], v[126:127] op_sel_hi:[0,1,1]
	v_pk_fma_f32 v[124:125], v[156:157], v[34:35], v[124:125] op_sel_hi:[0,1,1]
	v_pk_fma_f32 v[122:123], v[156:157], v[36:37], v[122:123] op_sel_hi:[0,1,1]
	v_pk_fma_f32 v[120:121], v[156:157], v[38:39], v[120:121] op_sel_hi:[0,1,1]
	v_cvt_pk_bf16_f32 v82, v94, v94
	global_store_short v[118:119], v82, off
	v_lshl_add_u64 v[118:119], s[8:9], 0, v[118:119]
	ds_read_b128 v[24:27], v154 offset:40704
	ds_read_b128 v[28:31], v154 offset:40720
	ds_read_b128 v[16:19], v154 offset:40448
	ds_read_b128 v[20:23], v154 offset:40464
	ds_read_b128 v[32:35], v154 offset:40960
	ds_read_b128 v[36:39], v154 offset:40976
	ds_read_b32 v116, v153 offset:41216
	s_waitcnt lgkmcnt(7)
	v_pk_mul_f32 v[156:157], v[64:65], v[126:127]
	v_pk_mul_f32 v[90:91], v[68:69], v[122:123]
	v_pk_mul_f32 v[158:159], v[0:1], v[126:127]
	v_pk_fma_f32 v[156:157], v[124:125], v[66:67], v[156:157]
	v_pk_fma_f32 v[90:91], v[120:121], v[70:71], v[90:91]
	v_pk_fma_f32 v[158:159], v[124:125], v[2:3], v[158:159]
	v_pk_fma_f32 v[126:127], v[128:129], v[56:57], v[126:127] op_sel_hi:[0,1,1]
	v_pk_fma_f32 v[158:159], v[122:123], v[4:5], v[158:159]
	v_pk_fma_f32 v[124:125], v[128:129], v[58:59], v[124:125] op_sel_hi:[0,1,1]
	v_pk_add_f32 v[156:157], v[156:157], v[90:91]
	v_pk_fma_f32 v[158:159], v[120:121], v[6:7], v[158:159]
	v_add_f32_e32 v155, v156, v157
	v_pk_fma_f32 v[122:123], v[128:129], v[60:61], v[122:123] op_sel_hi:[0,1,1]
	v_pk_fma_f32 v[120:121], v[128:129], v[62:63], v[120:121] op_sel_hi:[0,1,1]
	ds_read_b128 v[0:3], v154 offset:39936
	ds_read_b128 v[4:7], v154 offset:39952
	v_add_f32_e32 v158, v158, v159
	v_add_f32_dpp v155, v155, v155 quad_perm:[1,0,3,2] row_mask:0xf bank_mask:0xf bound_ctrl:1
	s_mov_b32 s6, 0x1010101
	s_mov_b32 s7, 0x1010101
	v_add_f32_dpp v158, v158, v158 quad_perm:[1,0,3,2] row_mask:0xf bank_mask:0xf bound_ctrl:1
	v_add_f32_dpp v155, v155, v155 quad_perm:[2,3,0,1] row_mask:0xf bank_mask:0xf bound_ctrl:1
	s_nop 0
	v_add_f32_dpp v158, v158, v158 quad_perm:[2,3,0,1] row_mask:0xf bank_mask:0xf bound_ctrl:1
	v_add_f32_dpp v156, v155, v155 row_half_mirror row_mask:0xf bank_mask:0xf bound_ctrl:1
	v_pk_fma_f32 v[126:127], v[156:157], v[72:73], v[126:127] op_sel_hi:[0,1,1]
	v_pk_fma_f32 v[124:125], v[156:157], v[74:75], v[124:125] op_sel_hi:[0,1,1]
	v_add_f32_dpp v158, v158, v158 row_half_mirror row_mask:0xf bank_mask:0xf bound_ctrl:1
	v_pk_fma_f32 v[122:123], v[156:157], v[76:77], v[122:123] op_sel_hi:[0,1,1]
	v_pk_fma_f32 v[120:121], v[156:157], v[78:79], v[120:121] op_sel_hi:[0,1,1]
	v_cndmask_b32_e64 v94, v94, v158, s[6:7]
	ds_read_b128 v[64:67], v154 offset:42240
	ds_read_b128 v[68:71], v154 offset:42256
	ds_read_b128 v[56:59], v154 offset:41984
	ds_read_b128 v[60:63], v154 offset:42000
	ds_read_b128 v[72:75], v154 offset:42496
	ds_read_b128 v[76:79], v154 offset:42512
	ds_read_b32 v128, v153 offset:42752
	s_waitcnt lgkmcnt(7)
	v_pk_mul_f32 v[156:157], v[24:25], v[126:127]
	v_pk_mul_f32 v[90:91], v[28:29], v[122:123]
	v_pk_mul_f32 v[158:159], v[40:41], v[126:127]
	v_pk_fma_f32 v[156:157], v[124:125], v[26:27], v[156:157]
	v_pk_fma_f32 v[90:91], v[120:121], v[30:31], v[90:91]
	v_pk_fma_f32 v[158:159], v[124:125], v[42:43], v[158:159]
	v_pk_fma_f32 v[126:127], v[116:117], v[16:17], v[126:127] op_sel_hi:[0,1,1]
	v_pk_fma_f32 v[158:159], v[122:123], v[44:45], v[158:159]
	v_pk_fma_f32 v[124:125], v[116:117], v[18:19], v[124:125] op_sel_hi:[0,1,1]
	v_pk_add_f32 v[156:157], v[156:157], v[90:91]
	v_pk_fma_f32 v[158:159], v[120:121], v[46:47], v[158:159]
	v_add_f32_e32 v155, v156, v157
	v_pk_fma_f32 v[122:123], v[116:117], v[20:21], v[122:123] op_sel_hi:[0,1,1]
	v_pk_fma_f32 v[120:121], v[116:117], v[22:23], v[120:121] op_sel_hi:[0,1,1]
	ds_read_b128 v[40:43], v154 offset:41472
	ds_read_b128 v[44:47], v154 offset:41488
	v_add_f32_e32 v158, v158, v159
	v_add_f32_dpp v155, v155, v155 quad_perm:[1,0,3,2] row_mask:0xf bank_mask:0xf bound_ctrl:1
	s_mov_b32 s6, 0x2020202
	s_mov_b32 s7, 0x2020202
	v_add_f32_dpp v158, v158, v158 quad_perm:[1,0,3,2] row_mask:0xf bank_mask:0xf bound_ctrl:1
	v_add_f32_dpp v155, v155, v155 quad_perm:[2,3,0,1] row_mask:0xf bank_mask:0xf bound_ctrl:1
	s_nop 0
	v_add_f32_dpp v158, v158, v158 quad_perm:[2,3,0,1] row_mask:0xf bank_mask:0xf bound_ctrl:1
	v_add_f32_dpp v156, v155, v155 row_half_mirror row_mask:0xf bank_mask:0xf bound_ctrl:1
	v_pk_fma_f32 v[126:127], v[156:157], v[32:33], v[126:127] op_sel_hi:[0,1,1]
	v_pk_fma_f32 v[124:125], v[156:157], v[34:35], v[124:125] op_sel_hi:[0,1,1]
	v_add_f32_dpp v158, v158, v158 row_half_mirror row_mask:0xf bank_mask:0xf bound_ctrl:1
	v_pk_fma_f32 v[122:123], v[156:157], v[36:37], v[122:123] op_sel_hi:[0,1,1]
	v_pk_fma_f32 v[120:121], v[156:157], v[38:39], v[120:121] op_sel_hi:[0,1,1]
	v_cndmask_b32_e64 v94, v94, v158, s[6:7]
	ds_read_b128 v[24:27], v154 offset:43776
	ds_read_b128 v[28:31], v154 offset:43792
	ds_read_b128 v[16:19], v154 offset:43520
	ds_read_b128 v[20:23], v154 offset:43536
	ds_read_b128 v[32:35], v154 offset:44032
	ds_read_b128 v[36:39], v154 offset:44048
	ds_read_b32 v116, v153 offset:44288
	s_waitcnt lgkmcnt(7)
; #define LAS __attribute__((address_space(3)))
; DI unsigned pack2(float lo, float hi) { f32x2 v = {lo, hi}; return __builtin_bit_cast(unsigned, __builtin_convertvector(v, bf16x2_t)); }
; DI void scan_item(PP p, int l, int item, LAS unsigned char* lds) {
;     ...
;     for (int c = 0; c < NCH; ++c) {
;         if (wid >= 4) { if (c + 1 < NCH) { fill(c + 1); if (c + 2 < NCH) gl(c + 2); } }
;         else {
;             const LAS float* sp = buf + ((c & 1) * T) * 384;
;             f32x4 Ar0, Ar1, Aw0, Aw1, Ak0, Ak1, Aa0, Aa1, Ab0, Ab1; float Avv;
;             f32x4 Br0, Br1, Bw0, Bw1, Bk0, Bk1, Ba0, Ba1, Bb0, Bb1; float Bvv;
;             SC_LD(A, sp);
;             const ptrdiff_t ystep = dir ? -512 : 512;
;             u16* Yl = Yp + (size_t)steprow(b, dir, c * T) * 512 + (ptrdiff_t)ks * ystep;
; #pragma nounroll
;             for (int st = 0; st < T; st += 2) {
;                 SC_LD(B, sp + (st + 1) * 384);
;                 SC_STEP(A, st);
;                 if (st + 2 < T) SC_LD(A, sp + (st + 2) * 384);
;                 SC_STEP(B, st + 1);
;                 if ((st & 6) == 6) {
;                     const LAS float* rp = ypl + (ks * 68 - lane) + (lane & ~7);
;                     const f32x4 q0 = *(const LAS f32x4*)rp, q1 = *(const LAS f32x4*)(rp + 4);
;                     Yl[(ptrdiff_t)(st - 6) * ystep] = (u16)(pack2(((q0[0] + q0[1]) + (q0[2] + q0[3])) + ((q1[0] + q1[1]) + (q1[2] + q1[3])), 0.f) & 0xffffu);
;                 }
;             }
	v_pk_mul_f32 v[156:157], v[64:65], v[126:127]
	v_pk_mul_f32 v[90:91], v[68:69], v[122:123]
	v_pk_mul_f32 v[158:159], v[0:1], v[126:127]
	v_pk_fma_f32 v[156:157], v[124:125], v[66:67], v[156:157]
	v_pk_fma_f32 v[90:91], v[120:121], v[70:71], v[90:91]
	v_pk_fma_f32 v[158:159], v[124:125], v[2:3], v[158:159]
	v_pk_fma_f32 v[126:127], v[128:129], v[56:57], v[126:127] op_sel_hi:[0,1,1]
	v_pk_fma_f32 v[158:159], v[122:123], v[4:5], v[158:159]
	v_pk_fma_f32 v[124:125], v[128:129], v[58:59], v[124:125] op_sel_hi:[0,1,1]
	v_pk_add_f32 v[156:157], v[156:157], v[90:91]
	v_pk_fma_f32 v[158:159], v[120:121], v[6:7], v[158:159]
	v_add_f32_e32 v155, v156, v157
	v_pk_fma_f32 v[122:123], v[128:129], v[60:61], v[122:123] op_sel_hi:[0,1,1]
	v_pk_fma_f32 v[120:121], v[128:129], v[62:63], v[120:121] op_sel_hi:[0,1,1]
	ds_read_b128 v[0:3], v154 offset:43008
	ds_read_b128 v[4:7], v154 offset:43024
	v_add_f32_e32 v158, v158, v159
	v_add_f32_dpp v155, v155, v155 quad_perm:[1,0,3,2] row_mask:0xf bank_mask:0xf bound_ctrl:1
	s_mov_b32 s6, 0x4040404
	s_mov_b32 s7, 0x4040404
	v_add_f32_dpp v158, v158, v158 quad_perm:[1,0,3,2] row_mask:0xf bank_mask:0xf bound_ctrl:1
	v_add_f32_dpp v155, v155, v155 quad_perm:[2,3,0,1] row_mask:0xf bank_mask:0xf bound_ctrl:1
	s_nop 0
	v_add_f32_dpp v158, v158, v158 quad_perm:[2,3,0,1] row_mask:0xf bank_mask:0xf bound_ctrl:1
	v_add_f32_dpp v156, v155, v155 row_half_mirror row_mask:0xf bank_mask:0xf bound_ctrl:1
	v_pk_fma_f32 v[126:127], v[156:157], v[72:73], v[126:127] op_sel_hi:[0,1,1]
	v_pk_fma_f32 v[124:125], v[156:157], v[74:75], v[124:125] op_sel_hi:[0,1,1]
	v_add_f32_dpp v158, v158, v158 row_half_mirror row_mask:0xf bank_mask:0xf bound_ctrl:1
	v_pk_fma_f32 v[122:123], v[156:157], v[76:77], v[122:123] op_sel_hi:[0,1,1]
	v_pk_fma_f32 v[120:121], v[156:157], v[78:79], v[120:121] op_sel_hi:[0,1,1]
	v_cndmask_b32_e64 v94, v94, v158, s[6:7]
	ds_read_b128 v[64:67], v154 offset:45312
	ds_read_b128 v[68:71], v154 offset:45328
	ds_read_b128 v[56:59], v154 offset:45056
	ds_read_b128 v[60:63], v154 offset:45072
	ds_read_b128 v[72:75], v154 offset:45568
	ds_read_b128 v[76:79], v154 offset:45584
	ds_read_b32 v128, v153 offset:45824
	s_waitcnt lgkmcnt(7)
	v_pk_mul_f32 v[156:157], v[24:25], v[126:127]
	v_pk_mul_f32 v[90:91], v[28:29], v[122:123]
	v_pk_mul_f32 v[158:159], v[40:41], v[126:127]
	v_pk_fma_f32 v[156:157], v[124:125], v[26:27], v[156:157]
	v_pk_fma_f32 v[90:91], v[120:121], v[30:31], v[90:91]
	v_pk_fma_f32 v[158:159], v[124:125], v[42:43], v[158:159]
	v_pk_fma_f32 v[126:127], v[116:117], v[16:17], v[126:127] op_sel_hi:[0,1,1]
	v_pk_fma_f32 v[158:159], v[122:123], v[44:45], v[158:159]
	v_pk_fma_f32 v[124:125], v[116:117], v[18:19], v[124:125] op_sel_hi:[0,1,1]
	v_pk_add_f32 v[156:157], v[156:157], v[90:91]
	v_pk_fma_f32 v[158:159], v[120:121], v[46:47], v[158:159]
	v_add_f32_e32 v155, v156, v157
	v_pk_fma_f32 v[122:123], v[116:117], v[20:21], v[122:123] op_sel_hi:[0,1,1]
	v_pk_fma_f32 v[120:121], v[116:117], v[22:23], v[120:121] op_sel_hi:[0,1,1]
	ds_read_b128 v[40:43], v154 offset:44544
	ds_read_b128 v[44:47], v154 offset:44560
	v_add_f32_e32 v158, v158, v159
	v_add_f32_dpp v155, v155, v155 quad_perm:[1,0,3,2] row_mask:0xf bank_mask:0xf bound_ctrl:1
	s_mov_b32 s6, 0x8080808
	s_mov_b32 s7, 0x8080808
	v_add_f32_dpp v158, v158, v158 quad_perm:[1,0,3,2] row_mask:0xf bank_mask:0xf bound_ctrl:1
	v_add_f32_dpp v155, v155, v155 quad_perm:[2,3,0,1] row_mask:0xf bank_mask:0xf bound_ctrl:1
	s_nop 0
	v_add_f32_dpp v158, v158, v158 quad_perm:[2,3,0,1] row_mask:0xf bank_mask:0xf bound_ctrl:1
	v_add_f32_dpp v156, v155, v155 row_half_mirror row_mask:0xf bank_mask:0xf bound_ctrl:1
	v_pk_fma_f32 v[126:127], v[156:157], v[32:33], v[126:127] op_sel_hi:[0,1,1]
	v_pk_fma_f32 v[124:125], v[156:157], v[34:35], v[124:125] op_sel_hi:[0,1,1]
	v_add_f32_dpp v158, v158, v158 row_half_mirror row_mask:0xf bank_mask:0xf bound_ctrl:1
	v_pk_fma_f32 v[122:123], v[156:157], v[36:37], v[122:123] op_sel_hi:[0,1,1]
	v_pk_fma_f32 v[120:121], v[156:157], v[38:39], v[120:121] op_sel_hi:[0,1,1]
	v_cndmask_b32_e64 v94, v94, v158, s[6:7]
	ds_read_b128 v[24:27], v154 offset:46848
	ds_read_b128 v[28:31], v154 offset:46864
	ds_read_b128 v[16:19], v154 offset:46592
	ds_read_b128 v[20:23], v154 offset:46608
	ds_read_b128 v[32:35], v154 offset:47104
	ds_read_b128 v[36:39], v154 offset:47120
	ds_read_b32 v116, v153 offset:47360
	s_waitcnt lgkmcnt(7)
	v_pk_mul_f32 v[156:157], v[64:65], v[126:127]
	v_pk_mul_f32 v[90:91], v[68:69], v[122:123]
	v_pk_mul_f32 v[158:159], v[0:1], v[126:127]
	v_pk_fma_f32 v[156:157], v[124:125], v[66:67], v[156:157]
	v_pk_fma_f32 v[90:91], v[120:121], v[70:71], v[90:91]
	v_pk_fma_f32 v[158:159], v[124:125], v[2:3], v[158:159]
	v_pk_fma_f32 v[126:127], v[128:129], v[56:57], v[126:127] op_sel_hi:[0,1,1]
	v_pk_fma_f32 v[158:159], v[122:123], v[4:5], v[158:159]
	v_pk_fma_f32 v[124:125], v[128:129], v[58:59], v[124:125] op_sel_hi:[0,1,1]
	v_pk_add_f32 v[156:157], v[156:157], v[90:91]
	v_pk_fma_f32 v[158:159], v[120:121], v[6:7], v[158:159]
	v_add_f32_e32 v155, v156, v157
	v_pk_fma_f32 v[122:123], v[128:129], v[60:61], v[122:123] op_sel_hi:[0,1,1]
	v_pk_fma_f32 v[120:121], v[128:129], v[62:63], v[120:121] op_sel_hi:[0,1,1]
	ds_read_b128 v[0:3], v154 offset:46080
	ds_read_b128 v[4:7], v154 offset:46096
	v_add_f32_e32 v158, v158, v159
	v_add_f32_dpp v155, v155, v155 quad_perm:[1,0,3,2] row_mask:0xf bank_mask:0xf bound_ctrl:1
	s_mov_b32 s6, 0x10101010
	s_mov_b32 s7, 0x10101010
	v_add_f32_dpp v158, v158, v158 quad_perm:[1,0,3,2] row_mask:0xf bank_mask:0xf bound_ctrl:1
	v_add_f32_dpp v155, v155, v155 quad_perm:[2,3,0,1] row_mask:0xf bank_mask:0xf bound_ctrl:1
	s_nop 0
	v_add_f32_dpp v158, v158, v158 quad_perm:[2,3,0,1] row_mask:0xf bank_mask:0xf bound_ctrl:1
	v_add_f32_dpp v156, v155, v155 row_half_mirror row_mask:0xf bank_mask:0xf bound_ctrl:1
	v_pk_fma_f32 v[126:127], v[156:157], v[72:73], v[126:127] op_sel_hi:[0,1,1]
	v_pk_fma_f32 v[124:125], v[156:157], v[74:75], v[124:125] op_sel_hi:[0,1,1]
	v_add_f32_dpp v158, v158, v158 row_half_mirror row_mask:0xf bank_mask:0xf bound_ctrl:1
	v_pk_fma_f32 v[122:123], v[156:157], v[76:77], v[122:123] op_sel_hi:[0,1,1]
	v_pk_fma_f32 v[120:121], v[156:157], v[78:79], v[120:121] op_sel_hi:[0,1,1]
	v_cndmask_b32_e64 v94, v94, v158, s[6:7]
	ds_read_b128 v[64:67], v154 offset:48384
	ds_read_b128 v[68:71], v154 offset:48400
	ds_read_b128 v[56:59], v154 offset:48128
	ds_read_b128 v[60:63], v154 offset:48144
	ds_read_b128 v[72:75], v154 offset:48640
	ds_read_b128 v[76:79], v154 offset:48656
	ds_read_b32 v128, v153 offset:48896
	ds_read_b128 v[48:51], v154 offset:47872
	ds_read_b128 v[52:55], v154 offset:47888
	s_waitcnt lgkmcnt(9)
; #define LAS __attribute__((address_space(3)))
; DI unsigned pack2(float lo, float hi) { f32x2 v = {lo, hi}; return __builtin_bit_cast(unsigned, __builtin_convertvector(v, bf16x2_t)); }
; DI void scan_item(PP p, int l, int item, LAS unsigned char* lds) {
;     ...
;     for (int c = 0; c < NCH; ++c) {
;         if (wid >= 4) { if (c + 1 < NCH) { fill(c + 1); if (c + 2 < NCH) gl(c + 2); } }
;         else {
;             const LAS float* sp = buf + ((c & 1) * T) * 384;
;             f32x4 Ar0, Ar1, Aw0, Aw1, Ak0, Ak1, Aa0, Aa1, Ab0, Ab1; float Avv;
;             f32x4 Br0, Br1, Bw0, Bw1, Bk0, Bk1, Ba0, Ba1, Bb0, Bb1; float Bvv;
;             SC_LD(A, sp);
;             const ptrdiff_t ystep = dir ? -512 : 512;
;             u16* Yl = Yp + (size_t)steprow(b, dir, c * T) * 512 + (ptrdiff_t)ks * ystep;
; #pragma nounroll
;             for (int st = 0; st < T; st += 2) {
;                 SC_LD(B, sp + (st + 1) * 384);
;                 SC_STEP(A, st);
;                 if (st + 2 < T) SC_LD(A, sp + (st + 2) * 384);
;                 SC_STEP(B, st + 1);
;                 if ((st & 6) == 6) {
;                     const LAS float* rp = ypl + (ks * 68 - lane) + (lane & ~7);
;                     const f32x4 q0 = *(const LAS f32x4*)rp, q1 = *(const LAS f32x4*)(rp + 4);
;                     Yl[(ptrdiff_t)(st - 6) * ystep] = (u16)(pack2(((q0[0] + q0[1]) + (q0[2] + q0[3])) + ((q1[0] + q1[1]) + (q1[2] + q1[3])), 0.f) & 0xffffu);
;                 }
;             }
	v_pk_mul_f32 v[156:157], v[24:25], v[126:127]
	v_pk_mul_f32 v[90:91], v[28:29], v[122:123]
	v_pk_mul_f32 v[158:159], v[40:41], v[126:127]
	v_pk_fma_f32 v[156:157], v[124:125], v[26:27], v[156:157]
	v_pk_fma_f32 v[90:91], v[120:121], v[30:31], v[90:91]
	v_pk_fma_f32 v[158:159], v[124:125], v[42:43], v[158:159]
	v_pk_fma_f32 v[126:127], v[116:117], v[16:17], v[126:127] op_sel_hi:[0,1,1]
	v_pk_fma_f32 v[158:159], v[122:123], v[44:45], v[158:159]
	v_pk_fma_f32 v[124:125], v[116:117], v[18:19], v[124:125] op_sel_hi:[0,1,1]
	v_pk_add_f32 v[156:157], v[156:157], v[90:91]
	v_pk_fma_f32 v[158:159], v[120:121], v[46:47], v[158:159]
	v_add_f32_e32 v155, v156, v157
	v_pk_fma_f32 v[122:123], v[116:117], v[20:21], v[122:123] op_sel_hi:[0,1,1]
	v_pk_fma_f32 v[120:121], v[116:117], v[22:23], v[120:121] op_sel_hi:[0,1,1]
	ds_read_b128 v[40:43], v154 offset:47616
	ds_read_b128 v[44:47], v154 offset:47632
	v_add_f32_e32 v158, v158, v159
	v_add_f32_dpp v155, v155, v155 quad_perm:[1,0,3,2] row_mask:0xf bank_mask:0xf bound_ctrl:1
	s_mov_b32 s6, 0x20202020
	s_mov_b32 s7, 0x20202020
	v_add_f32_dpp v158, v158, v158 quad_perm:[1,0,3,2] row_mask:0xf bank_mask:0xf bound_ctrl:1
	v_add_f32_dpp v155, v155, v155 quad_perm:[2,3,0,1] row_mask:0xf bank_mask:0xf bound_ctrl:1
	s_nop 0
	v_add_f32_dpp v158, v158, v158 quad_perm:[2,3,0,1] row_mask:0xf bank_mask:0xf bound_ctrl:1
	v_add_f32_dpp v156, v155, v155 row_half_mirror row_mask:0xf bank_mask:0xf bound_ctrl:1
	v_pk_fma_f32 v[126:127], v[156:157], v[32:33], v[126:127] op_sel_hi:[0,1,1]
	v_pk_fma_f32 v[124:125], v[156:157], v[34:35], v[124:125] op_sel_hi:[0,1,1]
	v_add_f32_dpp v158, v158, v158 row_half_mirror row_mask:0xf bank_mask:0xf bound_ctrl:1
	v_pk_fma_f32 v[122:123], v[156:157], v[36:37], v[122:123] op_sel_hi:[0,1,1]
	v_pk_fma_f32 v[120:121], v[156:157], v[38:39], v[120:121] op_sel_hi:[0,1,1]
	v_cndmask_b32_e64 v94, v94, v158, s[6:7]
	s_waitcnt lgkmcnt(0)
	v_pk_mul_f32 v[156:157], v[64:65], v[126:127]
	v_pk_mul_f32 v[90:91], v[68:69], v[122:123]
	v_pk_mul_f32 v[158:159], v[0:1], v[126:127]
	v_pk_fma_f32 v[156:157], v[124:125], v[66:67], v[156:157]
	v_pk_fma_f32 v[90:91], v[120:121], v[70:71], v[90:91]
	v_pk_fma_f32 v[158:159], v[124:125], v[2:3], v[158:159]
	v_pk_fma_f32 v[126:127], v[128:129], v[56:57], v[126:127] op_sel_hi:[0,1,1]
	v_pk_fma_f32 v[158:159], v[122:123], v[4:5], v[158:159]
	v_pk_fma_f32 v[124:125], v[128:129], v[58:59], v[124:125] op_sel_hi:[0,1,1]
	v_pk_add_f32 v[156:157], v[156:157], v[90:91]
	v_pk_fma_f32 v[158:159], v[120:121], v[6:7], v[158:159]
	v_add_f32_e32 v155, v156, v157
	v_pk_fma_f32 v[122:123], v[128:129], v[60:61], v[122:123] op_sel_hi:[0,1,1]
	v_pk_fma_f32 v[120:121], v[128:129], v[62:63], v[120:121] op_sel_hi:[0,1,1]
	v_add_f32_e32 v158, v158, v159
	v_add_f32_dpp v155, v155, v155 quad_perm:[1,0,3,2] row_mask:0xf bank_mask:0xf bound_ctrl:1
	s_mov_b32 s6, 0x40404040
	s_mov_b32 s7, 0x40404040
	v_add_f32_dpp v158, v158, v158 quad_perm:[1,0,3,2] row_mask:0xf bank_mask:0xf bound_ctrl:1
	v_add_f32_dpp v155, v155, v155 quad_perm:[2,3,0,1] row_mask:0xf bank_mask:0xf bound_ctrl:1
	s_nop 0
	v_add_f32_dpp v158, v158, v158 quad_perm:[2,3,0,1] row_mask:0xf bank_mask:0xf bound_ctrl:1
	v_add_f32_dpp v156, v155, v155 row_half_mirror row_mask:0xf bank_mask:0xf bound_ctrl:1
	v_pk_fma_f32 v[126:127], v[156:157], v[72:73], v[126:127] op_sel_hi:[0,1,1]
	v_pk_fma_f32 v[124:125], v[156:157], v[74:75], v[124:125] op_sel_hi:[0,1,1]
	v_add_f32_dpp v158, v158, v158 row_half_mirror row_mask:0xf bank_mask:0xf bound_ctrl:1
	v_pk_fma_f32 v[122:123], v[156:157], v[76:77], v[122:123] op_sel_hi:[0,1,1]
	v_pk_fma_f32 v[120:121], v[156:157], v[78:79], v[120:121] op_sel_hi:[0,1,1]
	v_cndmask_b32_e64 v94, v94, v158, s[6:7]
	v_pk_mul_f32 v[158:159], v[40:41], v[126:127]
	s_nop 0
	v_pk_fma_f32 v[158:159], v[124:125], v[42:43], v[158:159]
	s_nop 0
	v_pk_fma_f32 v[158:159], v[122:123], v[44:45], v[158:159]
	s_nop 0
	v_pk_fma_f32 v[158:159], v[120:121], v[46:47], v[158:159]
	s_nop 0
	v_add_f32_e32 v158, v158, v159
	s_mov_b32 s6, 0x80808080
	s_mov_b32 s7, 0x80808080
	v_add_f32_dpp v158, v158, v158 quad_perm:[1,0,3,2] row_mask:0xf bank_mask:0xf bound_ctrl:1
	s_nop 1
	v_add_f32_dpp v158, v158, v158 quad_perm:[2,3,0,1] row_mask:0xf bank_mask:0xf bound_ctrl:1
	s_nop 1
	v_add_f32_dpp v158, v158, v158 row_half_mirror row_mask:0xf bank_mask:0xf bound_ctrl:1
	v_pk_mul_f32 v[126:127], v[48:49], v[126:127]
	v_pk_mul_f32 v[124:125], v[50:51], v[124:125]
	v_pk_mul_f32 v[122:123], v[52:53], v[122:123]
	v_pk_mul_f32 v[120:121], v[54:55], v[120:121]
	v_cndmask_b32_e64 v94, v94, v158, s[6:7]
	v_cvt_pk_bf16_f32 v82, v94, v94
	global_store_short v[118:119], v82, off
	s_setprio 0
